# v23: v21 plus the now-dead lgkmcnt waits removed from the FFN-up epilogue (no LDS ops remain there after the DPP change)
# speedup vs baseline: 1.0058x; 1.0058x over previous
; DI float silu_f(float x) { return x * __builtin_amdgcn_rcpf(1.f + __builtin_amdgcn_exp2f(-LOG2E * x)); }
; DI float rstd_of(float ssq, float inv_n) { return 1.0f / sqrtf(ssq * inv_n + EPS); }
; DI float acc_get_i(const acc_t* base, unsigned idx, float inv_scale) { return (float)(*(const acc_t*)((const char*)base + idx * 8u)) * inv_scale; }
;     DI void operator()(const f32x4 (&acc)[2][2][4][2], const Unit& u, int wr, int wc, int fr, int fq) const {
;     ...
;             const int c4 = c8 + 4 * n;
;             const f32x4 w0 = *(const f32x4*)(cw + c4), w1 = *(const f32x4*)(cw + DFF + c4), w2 = *(const f32x4*)(cw + 2 * DFF + c4), cbv = *(const f32x4*)(cb + c4);
; #pragma unroll
;             for (int ai = 0; ai < 2; ++ai) {
;                 f32x4 pg = {0.f, 0.f, 0.f, 0.f};
; #pragma unroll
;                 for (int m = 0; m < 4; ++m) { const int row = u.pm * BM + ai * HALF + wr * 64 + m * 16 + fr;
;                     const float rs = rstd_of(acc_get_i(ssq, (unsigned)row, 1.0f / SSQ_SCALE), 1.0f / DM);
;                     const f32x4 g = acc[ai][0][m][n] * rs, up = acc[ai][1][m][n] * rs;
;                     f32x4 a;
; #pragma unroll
;                     for (int j = 0; j < 4; ++j) { const float s1 = __shfl(fr == 15 ? pg[j] : g[j], src1), s2 = __shfl(fr >= 14 ? pg[j] : g[j], src2);
;                         a[j] = silu_f(cbv[j] + w0[j] * s2 + w1[j] * s1 + w2[j] * g[j]) * up[j]; }
.LBB0_3093:
	s_lshl_b32 s15, s0, 8
	s_add_i32 s15, s15, s80
	v_or_b32_e32 v194, s15, v209
	v_lshlrev_b32_e32 v96, 3, v194
	v_lshlrev_b64 v[142:143], 2, v[176:177]
	v_lshl_add_u64 v[178:179], s[54:55], 0, v[142:143]
	v_lshl_add_u64 v[134:135], s[62:63], 0, v[142:143]
	v_lshl_add_u64 v[138:139], s[64:65], 0, v[142:143]
	v_lshl_add_u64 v[180:181], s[56:57], 0, v[142:143]
	global_load_dwordx4 v[130:133], v[178:179], off
	global_load_dwordx4 v[142:145], v[180:181], off
	v_mul_lo_u32 v218, v194, s90
	global_load_dwordx4 v[134:137], v[134:135], off
	global_load_dwordx4 v[138:141], v[138:139], off
	global_load_dwordx2 v[236:237], v96, s[48:49]
	global_load_dwordx2 v[238:239], v96, s[48:49] offset:128
	global_load_dwordx2 v[240:241], v96, s[48:49] offset:256
	global_load_dwordx2 v[242:243], v96, s[48:49] offset:384
	global_load_dwordx2 v[246:247], v96, s[48:49] offset:1024
	global_load_dwordx2 v[250:251], v96, s[48:49] offset:1152
	global_load_dwordx2 v[146:147], v96, s[48:49] offset:1280
	global_load_dwordx2 v[148:149], v96, s[48:49] offset:1408
	s_waitcnt vmcnt(0)
	v_ffbh_u32_e32 v150, v237
	v_min_u32_e32 v150, 32, v150
	v_lshlrev_b64 v[236:237], v150, v[236:237]
	v_min_u32_e32 v236, 1, v236
	v_or_b32_e32 v236, v237, v236
	v_cvt_f32_u32_e32 v236, v236
	v_sub_u32_e32 v237, 32, v150
	v_ldexp_f32 v236, v236, v237
	v_mul_f32_e32 v236, 0x35800000, v236
	v_fmamk_f32 v236, v236, 0x3a800000, v222
	v_rsq_f32_e32 v237, v236
	s_nop 0
	v_mul_f32_e32 v150, v236, v237
	v_fma_f32 v150, -v150, v237, 1.0
	v_mul_f32_e32 v150, 0.5, v150
	v_fmac_f32_e32 v237, v150, v237
	v_ffbh_u32_e32 v150, v239
	v_min_u32_e32 v150, 32, v150
	v_lshlrev_b64 v[238:239], v150, v[238:239]
	v_min_u32_e32 v238, 1, v238
	v_or_b32_e32 v238, v239, v238
	v_cvt_f32_u32_e32 v238, v238
	v_sub_u32_e32 v239, 32, v150
	v_ldexp_f32 v238, v238, v239
	v_mul_f32_e32 v238, 0x35800000, v238
	v_fmamk_f32 v238, v238, 0x3a800000, v222
	v_rsq_f32_e32 v239, v238
	s_nop 0
	v_mul_f32_e32 v150, v238, v239
	v_fma_f32 v150, -v150, v239, 1.0
	v_mul_f32_e32 v150, 0.5, v150
	v_fmac_f32_e32 v239, v150, v239
	v_ffbh_u32_e32 v150, v241
	v_min_u32_e32 v150, 32, v150
	v_lshlrev_b64 v[240:241], v150, v[240:241]
	v_min_u32_e32 v240, 1, v240
	v_or_b32_e32 v240, v241, v240
	v_cvt_f32_u32_e32 v240, v240
	v_sub_u32_e32 v241, 32, v150
	v_ldexp_f32 v240, v240, v241
	v_mul_f32_e32 v240, 0x35800000, v240
	v_fmamk_f32 v240, v240, 0x3a800000, v222
	v_rsq_f32_e32 v241, v240
	s_nop 0
	v_mul_f32_e32 v150, v240, v241
	v_fma_f32 v150, -v150, v241, 1.0
	v_mul_f32_e32 v150, 0.5, v150
	v_fmac_f32_e32 v241, v150, v241
	v_ffbh_u32_e32 v150, v243
	v_min_u32_e32 v150, 32, v150
	v_lshlrev_b64 v[242:243], v150, v[242:243]
	v_min_u32_e32 v242, 1, v242
	v_or_b32_e32 v242, v243, v242
	v_cvt_f32_u32_e32 v242, v242
	v_sub_u32_e32 v243, 32, v150
	v_ldexp_f32 v242, v242, v243
	v_mul_f32_e32 v242, 0x35800000, v242
	v_fmamk_f32 v242, v242, 0x3a800000, v222
	v_rsq_f32_e32 v243, v242
	s_nop 0
	v_mul_f32_e32 v150, v242, v243
	v_fma_f32 v150, -v150, v243, 1.0
	v_mul_f32_e32 v150, 0.5, v150
	v_fmac_f32_e32 v243, v150, v243
	v_ffbh_u32_e32 v150, v247
	v_min_u32_e32 v150, 32, v150
	v_lshlrev_b64 v[246:247], v150, v[246:247]
	v_min_u32_e32 v246, 1, v246
	v_or_b32_e32 v246, v247, v246
	v_cvt_f32_u32_e32 v246, v246
	v_sub_u32_e32 v247, 32, v150
	v_ldexp_f32 v246, v246, v247
	v_mul_f32_e32 v246, 0x35800000, v246
	v_fmamk_f32 v246, v246, 0x3a800000, v222
	v_rsq_f32_e32 v247, v246
	s_nop 0
	v_mul_f32_e32 v150, v246, v247
	v_fma_f32 v150, -v150, v247, 1.0
	v_mul_f32_e32 v150, 0.5, v150
	v_fmac_f32_e32 v247, v150, v247
	v_ffbh_u32_e32 v150, v251
	v_min_u32_e32 v150, 32, v150
	v_lshlrev_b64 v[250:251], v150, v[250:251]
	v_min_u32_e32 v250, 1, v250
	v_or_b32_e32 v250, v251, v250
	v_cvt_f32_u32_e32 v250, v250
	v_sub_u32_e32 v251, 32, v150
	v_ldexp_f32 v250, v250, v251
	v_mul_f32_e32 v250, 0x35800000, v250
	v_fmamk_f32 v250, v250, 0x3a800000, v222
	v_rsq_f32_e32 v251, v250
	s_nop 0
	v_mul_f32_e32 v150, v250, v251
	v_fma_f32 v150, -v150, v251, 1.0
	v_mul_f32_e32 v150, 0.5, v150
	v_fmac_f32_e32 v251, v150, v251
	v_ffbh_u32_e32 v150, v147
	v_min_u32_e32 v150, 32, v150
	v_lshlrev_b64 v[146:147], v150, v[146:147]
	v_min_u32_e32 v146, 1, v146
	v_or_b32_e32 v146, v147, v146
	v_cvt_f32_u32_e32 v146, v146
	v_sub_u32_e32 v147, 32, v150
	v_ldexp_f32 v146, v146, v147
	v_mul_f32_e32 v146, 0x35800000, v146
	v_fmamk_f32 v146, v146, 0x3a800000, v222
	v_rsq_f32_e32 v147, v146
	s_nop 0
	v_mul_f32_e32 v150, v146, v147
	v_fma_f32 v150, -v150, v147, 1.0
	v_mul_f32_e32 v150, 0.5, v150
	v_fmac_f32_e32 v147, v150, v147
	v_ffbh_u32_e32 v150, v149
	v_min_u32_e32 v150, 32, v150
	v_lshlrev_b64 v[148:149], v150, v[148:149]
	v_min_u32_e32 v148, 1, v148
	v_or_b32_e32 v148, v149, v148
	v_cvt_f32_u32_e32 v148, v148
	v_sub_u32_e32 v149, 32, v150
	v_ldexp_f32 v148, v148, v149
	v_mul_f32_e32 v148, 0x35800000, v148
	v_fmamk_f32 v148, v148, 0x3a800000, v222
	v_rsq_f32_e32 v149, v148
	s_nop 0
	v_mul_f32_e32 v150, v148, v149
	v_fma_f32 v150, -v150, v149, 1.0
	v_mul_f32_e32 v150, 0.5, v150
	v_fmac_f32_e32 v149, v150, v149
	v_mov_b32_e32 v236, v237
	v_mov_b32_e32 v237, v239
	v_mov_b32_e32 v238, v241
	v_mov_b32_e32 v239, v243
	v_mov_b32_e32 v240, v247
	v_mov_b32_e32 v241, v251
	v_mov_b32_e32 v242, v147
	v_mov_b32_e32 v243, v149
	s_waitcnt vmcnt(0)
	v_mov_b32_e32 v148, v236
	v_pk_mul_f32 v[186:187], v[126:127], v[148:149] op_sel_hi:[1,0]
	v_pk_mul_f32 v[184:185], v[128:129], v[148:149] op_sel_hi:[1,0]
	v_mov_b32_e32 v188, 0
	v_mov_b32_dpp v188, v186 row_shr:1 row_mask:0xf bank_mask:0xf
	v_mov_b32_e32 v192, 0
	v_mov_b32_dpp v192, v186 row_shr:2 row_mask:0xf bank_mask:0xf
	v_mov_b32_e32 v189, 0
	v_mov_b32_dpp v189, v187 row_shr:1 row_mask:0xf bank_mask:0xf
	v_mov_b32_e32 v193, 0
	v_mov_b32_dpp v193, v187 row_shr:2 row_mask:0xf bank_mask:0xf
	v_mov_b32_e32 v182, 0
	v_mov_b32_dpp v182, v184 row_shr:1 row_mask:0xf bank_mask:0xf
	v_mov_b32_e32 v190, 0
	v_mov_b32_dpp v190, v184 row_shr:2 row_mask:0xf bank_mask:0xf
	v_mov_b32_e32 v183, 0
	v_mov_b32_dpp v183, v185 row_shr:1 row_mask:0xf bank_mask:0xf
	v_mov_b32_e32 v191, 0
	v_mov_b32_dpp v191, v185 row_shr:2 row_mask:0xf bank_mask:0xf
	v_pk_mul_f32 v[146:147], v[120:121], v[148:149] op_sel_hi:[1,0]
	v_pk_mul_f32 v[148:149], v[118:119], v[148:149] op_sel_hi:[1,0]
	s_and_saveexec_b64 s[0:1], s[40:41]
	s_xor_b64 s[0:1], exec, s[0:1]
	s_cbranch_execz .LBB0_3095
; DI unsigned pk2(float lo, float hi) { f32x2 v = {lo, hi}; bf16x2_t b = __builtin_convertvector(v, bf16x2_t); return __builtin_bit_cast(unsigned, b); }
; DI float silu_f(float x) { return x * __builtin_amdgcn_rcpf(1.f + __builtin_amdgcn_exp2f(-LOG2E * x)); }
; DI float rstd_of(float ssq, float inv_n) { return 1.0f / sqrtf(ssq * inv_n + EPS); }
; DI float acc_get_i(const acc_t* base, unsigned idx, float inv_scale) { return (float)(*(const acc_t*)((const char*)base + idx * 8u)) * inv_scale; }
; template <class T> DI T* boff(T* base, unsigned byte_off) { return (T*)((char*)base + byte_off); }
;     DI void operator()(const f32x4 (&acc)[2][2][4][2], const Unit& u, int wr, int wc, int fr, int fq) const {
;     ...
;                 for (int m = 0; m < 4; ++m) { const int row = u.pm * BM + ai * HALF + wr * 64 + m * 16 + fr;
;                     const float rs = rstd_of(acc_get_i(ssq, (unsigned)row, 1.0f / SSQ_SCALE), 1.0f / DM);
;                     const f32x4 g = acc[ai][0][m][n] * rs, up = acc[ai][1][m][n] * rs;
;                     f32x4 a;
; #pragma unroll
;                     for (int j = 0; j < 4; ++j) { const float s1 = __shfl(fr == 15 ? pg[j] : g[j], src1), s2 = __shfl(fr >= 14 ? pg[j] : g[j], src2);
;                         a[j] = silu_f(cbv[j] + w0[j] * s2 + w1[j] * s1 + w2[j] * g[j]) * up[j]; }
;                     u32x2 gw; gw.x = pk2(g[0], g[1]); gw.y = pk2(g[2], g[3]);
;                     if (m == 0 && fr < 2) {
;                         *boff((u32x2*)GS, (unsigned)(((row >> 6) * 4 + 2 + fr) * DFF + c4) * 2u) = gw;
;                         u32x2 uw; uw.x = pk2(up[0], up[1]); uw.y = pk2(up[2], up[3]); *boff((u32x2*)US, (unsigned)(((row >> 6) * 2 + fr) * DFF + c4) * 2u) = uw;
;                     } else { u32x2 w; w.x = pk2(a[0], a[1]); w.y = pk2(a[2], a[3]); *boff((u32x2*)A2, (unsigned)(row * DFF + c4) * 2u) = w; }
;                     if (m == 3 && fr >= 14) {
;                         *boff((u32x2*)GS, (unsigned)(((row >> 6) * 4 + (fr - 14)) * DFF + c4) * 2u) = gw;
;                         if ((row & (SEQ - 1)) >= SEQ - 2) *boff((f32x4*)fcp, (unsigned)(((row >> 11) * 2 + ((row & (SEQ - 1)) - (SEQ - 2))) * DFF + c4) * 4u) = g;
;                     }
	v_pk_fma_f32 v[150:151], v[130:131], v[192:193], v[142:143]
	s_nop 0
	v_pk_fma_f32 v[150:151], v[134:135], v[188:189], v[150:151]
	v_pk_fma_f32 v[188:189], v[132:133], v[190:191], v[144:145]
	s_waitcnt vmcnt(0)
	v_pk_fma_f32 v[150:151], v[138:139], v[186:187], v[150:151]
	v_pk_fma_f32 v[182:183], v[136:137], v[182:183], v[188:189]
	v_mul_f32_e32 v152, 0xbfb8aa3b, v150
	v_mul_f32_e32 v153, 0xbfb8aa3b, v151
	v_pk_fma_f32 v[182:183], v[140:141], v[184:185], v[182:183]
	v_exp_f32_e32 v152, v152
	v_exp_f32_e32 v153, v153
	v_mul_f32_e32 v188, 0xbfb8aa3b, v182
	v_mul_f32_e32 v189, 0xbfb8aa3b, v183
	v_exp_f32_e32 v188, v188
	v_exp_f32_e32 v189, v189
	v_add_f32_e32 v152, 1.0, v152
	v_add_f32_e32 v153, 1.0, v153
	v_rcp_f32_e32 v152, v152
	v_rcp_f32_e32 v153, v153
	v_add_f32_e32 v188, 1.0, v188
	v_add_f32_e32 v189, 1.0, v189
	v_rcp_f32_e32 v188, v188
	v_rcp_f32_e32 v189, v189
	v_pk_mul_f32 v[150:151], v[150:151], v[152:153]
	s_nop 0
	v_pk_mul_f32 v[148:149], v[148:149], v[150:151]
	v_pk_mul_f32 v[150:151], v[182:183], v[188:189]
	v_cvt_pk_bf16_f32 v148, v148, v149
	v_pk_mul_f32 v[146:147], v[146:147], v[150:151]
	s_nop 0
	v_cvt_pk_bf16_f32 v149, v146, v147
	v_add_lshl_u32 v146, v218, v176, 1
	global_store_dwordx2 v146, v[148:149], s[46:47]
.LBB0_3095:
	s_or_saveexec_b64 s[0:1], s[0:1]
	s_ashr_i32 s2, s15, 4
	v_add_u32_e32 v150, s2, v209
	s_lshr_b32 s3, s15, 5
	v_mul_lo_u32 v183, v150, s90
	v_add_u32_e32 v150, s3, v209
	v_add_u32_e32 v202, 0x1600, v176
	v_mul_lo_u32 v219, v150, s90
	s_xor_b64 exec, exec, s[0:1]
	s_cbranch_execz .LBB0_3097
	v_cvt_pk_bf16_f32 v150, v186, v187
	v_cvt_pk_bf16_f32 v151, v184, v185
	v_add_lshl_u32 v152, v219, v176, 1
	v_add_lshl_u32 v153, v183, v202, 1
	v_cvt_pk_bf16_f32 v148, v148, v149
	v_cvt_pk_bf16_f32 v149, v146, v147
	global_store_dwordx2 v153, v[150:151], s[50:51]
	global_store_dwordx2 v152, v[148:149], s[52:53]
.LBB0_3097:
	s_or_b64 exec, exec, s[0:1]
	v_or_b32_e32 v192, 16, v194
	v_add_u32_e32 v146, s2, v212
	v_lshlrev_b32_e32 v182, 3, v192
	v_mul_lo_u32 v217, v146, s90
	s_ashr_i32 s0, s15, 10
	s_and_b32 s14, s0, 0x3ffffffe
	s_add_i32 s14, s14, 0x3ffff802
	v_mov_b32_e32 v150, v237
	v_pk_mul_f32 v[148:149], v[110:111], v[150:151] op_sel_hi:[1,0]
	v_pk_mul_f32 v[146:147], v[112:113], v[150:151] op_sel_hi:[1,0]
	v_mov_b32_dpp v152, v186 row_ror:1 row_mask:0xf bank_mask:0xf
	v_mov_b32_dpp v152, v148 row_shr:1 row_mask:0xf bank_mask:0xf
	v_mov_b32_dpp v186, v186 row_ror:2 row_mask:0xf bank_mask:0xf
	v_mov_b32_dpp v186, v148 row_shr:2 row_mask:0xf bank_mask:0xf
	v_mov_b32_dpp v153, v187 row_ror:1 row_mask:0xf bank_mask:0xf
	v_mov_b32_dpp v153, v149 row_shr:1 row_mask:0xf bank_mask:0xf
	v_mov_b32_dpp v187, v187 row_ror:2 row_mask:0xf bank_mask:0xf
	v_mov_b32_dpp v187, v149 row_shr:2 row_mask:0xf bank_mask:0xf
	v_mov_b32_dpp v188, v184 row_ror:1 row_mask:0xf bank_mask:0xf
	v_mov_b32_dpp v188, v146 row_shr:1 row_mask:0xf bank_mask:0xf
	v_mov_b32_dpp v184, v184 row_ror:2 row_mask:0xf bank_mask:0xf
	v_mov_b32_dpp v184, v146 row_shr:2 row_mask:0xf bank_mask:0xf
	v_pk_fma_f32 v[186:187], v[130:131], v[186:187], v[142:143]
	v_mov_b32_dpp v189, v185 row_ror:1 row_mask:0xf bank_mask:0xf
	v_mov_b32_dpp v189, v147 row_shr:1 row_mask:0xf bank_mask:0xf
	v_pk_fma_f32 v[152:153], v[134:135], v[152:153], v[186:187]
	v_pk_fma_f32 v[152:153], v[138:139], v[148:149], v[152:153]
	v_mov_b32_dpp v185, v185 row_ror:2 row_mask:0xf bank_mask:0xf
	v_mov_b32_dpp v185, v147 row_shr:2 row_mask:0xf bank_mask:0xf
	v_mul_f32_e32 v186, 0xbfb8aa3b, v152
	v_mul_f32_e32 v187, 0xbfb8aa3b, v153
	v_exp_f32_e32 v186, v186
	v_exp_f32_e32 v187, v187
	v_pk_mul_f32 v[190:191], v[104:105], v[150:151] op_sel_hi:[1,0]
	v_add_f32_e32 v186, 1.0, v186
	v_add_f32_e32 v187, 1.0, v187
	v_rcp_f32_e32 v186, v186
	v_rcp_f32_e32 v187, v187
	v_pk_mul_f32 v[150:151], v[102:103], v[150:151] op_sel_hi:[1,0]
	v_pk_mul_f32 v[152:153], v[152:153], v[186:187]
	s_nop 0
	v_pk_mul_f32 v[150:151], v[150:151], v[152:153]
	v_pk_fma_f32 v[152:153], v[132:133], v[184:185], v[144:145]
	v_mul_lo_u32 v187, v192, s90
	v_pk_fma_f32 v[152:153], v[136:137], v[188:189], v[152:153]
	v_cvt_pk_bf16_f32 v150, v150, v151
	v_pk_fma_f32 v[152:153], v[140:141], v[146:147], v[152:153]
	v_add_u32_e32 v220, 0xb000, v187
	v_mul_f32_e32 v184, 0xbfb8aa3b, v152
	v_mul_f32_e32 v185, 0xbfb8aa3b, v153
	v_exp_f32_e32 v184, v184
	v_exp_f32_e32 v185, v185
	v_add_u32_e32 v230, 0x16000, v187
	v_add_f32_e32 v184, 1.0, v184
	v_add_f32_e32 v185, 1.0, v185
	v_rcp_f32_e32 v184, v184
	v_rcp_f32_e32 v185, v185
	s_nop 0
	v_pk_mul_f32 v[152:153], v[152:153], v[184:185]
	s_nop 0
	v_pk_mul_f32 v[152:153], v[190:191], v[152:153]
	v_lshl_or_b32 v184, v194, 3, v229
	v_cvt_pk_bf16_f32 v151, v152, v153
	v_add_lshl_u32 v152, v187, v176, 1
	global_store_dwordx2 v152, v[150:151], s[46:47]
	v_mov_b32_e32 v150, v238
	v_pk_mul_f32 v[190:191], v[92:93], v[150:151] op_sel_hi:[1,0]
	v_pk_mul_f32 v[188:189], v[94:95], v[150:151] op_sel_hi:[1,0]
	v_mov_b32_dpp v152, v148 row_ror:1 row_mask:0xf bank_mask:0xf
	v_mov_b32_dpp v152, v190 row_shr:1 row_mask:0xf bank_mask:0xf
	v_mov_b32_dpp v148, v148 row_ror:2 row_mask:0xf bank_mask:0xf
	v_mov_b32_dpp v148, v190 row_shr:2 row_mask:0xf bank_mask:0xf
	v_mov_b32_dpp v153, v149 row_ror:1 row_mask:0xf bank_mask:0xf
	v_mov_b32_dpp v153, v191 row_shr:1 row_mask:0xf bank_mask:0xf
	v_mov_b32_dpp v192, v146 row_ror:1 row_mask:0xf bank_mask:0xf
	v_mov_b32_dpp v192, v188 row_shr:1 row_mask:0xf bank_mask:0xf
	v_mov_b32_dpp v146, v146 row_ror:2 row_mask:0xf bank_mask:0xf
	v_mov_b32_dpp v146, v188 row_shr:2 row_mask:0xf bank_mask:0xf
	v_mov_b32_dpp v149, v149 row_ror:2 row_mask:0xf bank_mask:0xf
; DI unsigned pk2(float lo, float hi) { f32x2 v = {lo, hi}; bf16x2_t b = __builtin_convertvector(v, bf16x2_t); return __builtin_bit_cast(unsigned, b); }
; DI float silu_f(float x) { return x * __builtin_amdgcn_rcpf(1.f + __builtin_amdgcn_exp2f(-LOG2E * x)); }
; DI float rstd_of(float ssq, float inv_n) { return 1.0f / sqrtf(ssq * inv_n + EPS); }
; DI float acc_get_i(const acc_t* base, unsigned idx, float inv_scale) { return (float)(*(const acc_t*)((const char*)base + idx * 8u)) * inv_scale; }
; template <class T> DI T* boff(T* base, unsigned byte_off) { return (T*)((char*)base + byte_off); }
;     DI void operator()(const f32x4 (&acc)[2][2][4][2], const Unit& u, int wr, int wc, int fr, int fq) const {
;     ...
;                 for (int m = 0; m < 4; ++m) { const int row = u.pm * BM + ai * HALF + wr * 64 + m * 16 + fr;
;                     const float rs = rstd_of(acc_get_i(ssq, (unsigned)row, 1.0f / SSQ_SCALE), 1.0f / DM);
;                     const f32x4 g = acc[ai][0][m][n] * rs, up = acc[ai][1][m][n] * rs;
;                     f32x4 a;
; #pragma unroll
;                     for (int j = 0; j < 4; ++j) { const float s1 = __shfl(fr == 15 ? pg[j] : g[j], src1), s2 = __shfl(fr >= 14 ? pg[j] : g[j], src2);
;                         a[j] = silu_f(cbv[j] + w0[j] * s2 + w1[j] * s1 + w2[j] * g[j]) * up[j]; }
;                     u32x2 gw; gw.x = pk2(g[0], g[1]); gw.y = pk2(g[2], g[3]);
;                     if (m == 0 && fr < 2) {
;                         *boff((u32x2*)GS, (unsigned)(((row >> 6) * 4 + 2 + fr) * DFF + c4) * 2u) = gw;
;                         u32x2 uw; uw.x = pk2(up[0], up[1]); uw.y = pk2(up[2], up[3]); *boff((u32x2*)US, (unsigned)(((row >> 6) * 2 + fr) * DFF + c4) * 2u) = uw;
;                     } else { u32x2 w; w.x = pk2(a[0], a[1]); w.y = pk2(a[2], a[3]); *boff((u32x2*)A2, (unsigned)(row * DFF + c4) * 2u) = w; }
;                     if (m == 3 && fr >= 14) {
;                         *boff((u32x2*)GS, (unsigned)(((row >> 6) * 4 + (fr - 14)) * DFF + c4) * 2u) = gw;
;                         if ((row & (SEQ - 1)) >= SEQ - 2) *boff((f32x4*)fcp, (unsigned)(((row >> 11) * 2 + ((row & (SEQ - 1)) - (SEQ - 2))) * DFF + c4) * 4u) = g;
;                     }
	v_mov_b32_dpp v149, v191 row_shr:2 row_mask:0xf bank_mask:0xf
	v_pk_fma_f32 v[148:149], v[130:131], v[148:149], v[142:143]
	v_mov_b32_dpp v193, v147 row_ror:1 row_mask:0xf bank_mask:0xf
	v_mov_b32_dpp v193, v189 row_shr:1 row_mask:0xf bank_mask:0xf
	v_pk_fma_f32 v[148:149], v[134:135], v[152:153], v[148:149]
	v_mov_b32_dpp v147, v147 row_ror:2 row_mask:0xf bank_mask:0xf
	v_mov_b32_dpp v147, v189 row_shr:2 row_mask:0xf bank_mask:0xf
	v_pk_fma_f32 v[148:149], v[138:139], v[190:191], v[148:149]
	v_mul_f32_e32 v152, 0xbfb8aa3b, v148
	v_mul_f32_e32 v153, 0xbfb8aa3b, v149
	v_exp_f32_e32 v152, v152
	v_exp_f32_e32 v153, v153
	v_add_f32_e32 v152, 1.0, v152
	v_add_f32_e32 v153, 1.0, v153
	v_rcp_f32_e32 v152, v152
	v_rcp_f32_e32 v153, v153
	v_pk_fma_f32 v[146:147], v[132:133], v[146:147], v[144:145]
	v_pk_mul_f32 v[196:197], v[86:87], v[150:151] op_sel_hi:[1,0]
	v_pk_fma_f32 v[146:147], v[136:137], v[192:193], v[146:147]
	v_pk_mul_f32 v[150:151], v[84:85], v[150:151] op_sel_hi:[1,0]
	v_pk_mul_f32 v[148:149], v[148:149], v[152:153]
	v_pk_fma_f32 v[146:147], v[140:141], v[188:189], v[146:147]
	v_pk_mul_f32 v[148:149], v[150:151], v[148:149]
	v_mul_f32_e32 v150, 0xbfb8aa3b, v146
	v_mul_f32_e32 v151, 0xbfb8aa3b, v147
	v_exp_f32_e32 v150, v150
	v_exp_f32_e32 v151, v151
	v_cvt_pk_bf16_f32 v148, v148, v149
	v_or_b32_e32 v185, 48, v194
	v_add_f32_e32 v150, 1.0, v150
	v_add_f32_e32 v151, 1.0, v151
	v_rcp_f32_e32 v150, v150
	v_rcp_f32_e32 v151, v151
	v_lshlrev_b32_e32 v186, 3, v185
	v_pk_mul_f32 v[146:147], v[146:147], v[150:151]
	s_nop 0
	v_pk_mul_f32 v[146:147], v[196:197], v[146:147]
	s_nop 0
	v_cvt_pk_bf16_f32 v149, v146, v147
	v_add_lshl_u32 v146, v220, v176, 1
	global_store_dwordx2 v146, v[148:149], s[46:47]
	v_mov_b32_e32 v150, v239
	v_pk_mul_f32 v[146:147], v[76:77], v[150:151] op_sel_hi:[1,0]
	v_pk_mul_f32 v[148:149], v[78:79], v[150:151] op_sel_hi:[1,0]
	v_mov_b32_dpp v152, v190 row_ror:1 row_mask:0xf bank_mask:0xf
	v_mov_b32_dpp v152, v146 row_shr:1 row_mask:0xf bank_mask:0xf
	v_mov_b32_dpp v190, v190 row_ror:2 row_mask:0xf bank_mask:0xf
	v_mov_b32_dpp v190, v146 row_shr:2 row_mask:0xf bank_mask:0xf
	v_mov_b32_dpp v153, v191 row_ror:1 row_mask:0xf bank_mask:0xf
	v_mov_b32_dpp v153, v147 row_shr:1 row_mask:0xf bank_mask:0xf
	v_mov_b32_dpp v191, v191 row_ror:2 row_mask:0xf bank_mask:0xf
	v_mov_b32_dpp v191, v147 row_shr:2 row_mask:0xf bank_mask:0xf
	v_mov_b32_dpp v192, v188 row_ror:1 row_mask:0xf bank_mask:0xf
	v_mov_b32_dpp v192, v148 row_shr:1 row_mask:0xf bank_mask:0xf
	v_mov_b32_dpp v188, v188 row_ror:2 row_mask:0xf bank_mask:0xf
	v_mov_b32_dpp v188, v148 row_shr:2 row_mask:0xf bank_mask:0xf
	v_pk_fma_f32 v[190:191], v[130:131], v[190:191], v[142:143]
	v_mov_b32_dpp v193, v189 row_ror:1 row_mask:0xf bank_mask:0xf
	v_mov_b32_dpp v193, v149 row_shr:1 row_mask:0xf bank_mask:0xf
	v_pk_fma_f32 v[152:153], v[134:135], v[152:153], v[190:191]
	v_pk_fma_f32 v[152:153], v[138:139], v[146:147], v[152:153]
	v_mov_b32_dpp v189, v189 row_ror:2 row_mask:0xf bank_mask:0xf
	v_mov_b32_dpp v189, v149 row_shr:2 row_mask:0xf bank_mask:0xf
	v_mul_f32_e32 v190, 0xbfb8aa3b, v152
	v_mul_f32_e32 v191, 0xbfb8aa3b, v153
	v_exp_f32_e32 v190, v190
	v_exp_f32_e32 v191, v191
	v_pk_mul_f32 v[194:195], v[70:71], v[150:151] op_sel_hi:[1,0]
	v_add_f32_e32 v190, 1.0, v190
	v_add_f32_e32 v191, 1.0, v191
	v_rcp_f32_e32 v190, v190
	v_rcp_f32_e32 v191, v191
	v_pk_mul_f32 v[150:151], v[68:69], v[150:151] op_sel_hi:[1,0]
	v_pk_mul_f32 v[152:153], v[152:153], v[190:191]
	s_nop 0
	v_pk_mul_f32 v[150:151], v[150:151], v[152:153]
	v_pk_fma_f32 v[152:153], v[132:133], v[188:189], v[144:145]
	s_nop 0
	v_pk_fma_f32 v[152:153], v[136:137], v[192:193], v[152:153]
	s_nop 0
	v_pk_fma_f32 v[152:153], v[140:141], v[148:149], v[152:153]
	s_nop 0
	v_mul_f32_e32 v188, 0xbfb8aa3b, v152
	v_mul_f32_e32 v189, 0xbfb8aa3b, v153
	v_exp_f32_e32 v188, v188
	v_exp_f32_e32 v189, v189
	v_add_f32_e32 v188, 1.0, v188
	v_add_f32_e32 v189, 1.0, v189
	v_rcp_f32_e32 v188, v188
	v_rcp_f32_e32 v189, v189
	s_nop 0
	v_pk_mul_f32 v[152:153], v[152:153], v[188:189]
	s_nop 0
	v_pk_mul_f32 v[152:153], v[194:195], v[152:153]
	v_cvt_pk_bf16_f32 v188, v150, v151
	v_cvt_pk_bf16_f32 v189, v152, v153
	v_add_lshl_u32 v150, v230, v176, 1
	global_store_dwordx2 v150, v[188:189], s[46:47]
	v_and_b32_e32 v189, 0x7ff, v185
	s_and_saveexec_b64 s[0:1], s[38:39]
	s_cbranch_execz .LBB0_3100
	s_movk_i32 s2, 0x7fd
	v_add_lshl_u32 v152, v217, v176, 1
	v_cvt_pk_bf16_f32 v150, v146, v147
	v_cvt_pk_bf16_f32 v151, v148, v149
	v_cmp_lt_u32_e32 vcc, s2, v189
	global_store_dwordx2 v152, v[150:151], s[50:51]
	s_and_b64 exec, exec, vcc
	s_cbranch_execz .LBB0_3100
	v_add_u32_e32 v150, s14, v189
	v_mul_lo_u32 v150, v150, s90
	v_add_lshl_u32 v150, v150, v176, 2
	global_store_dwordx4 v150, v[146:149], s[58:59]
; DI unsigned pk2(float lo, float hi) { f32x2 v = {lo, hi}; bf16x2_t b = __builtin_convertvector(v, bf16x2_t); return __builtin_bit_cast(unsigned, b); }
; DI float silu_f(float x) { return x * __builtin_amdgcn_rcpf(1.f + __builtin_amdgcn_exp2f(-LOG2E * x)); }
; DI float rstd_of(float ssq, float inv_n) { return 1.0f / sqrtf(ssq * inv_n + EPS); }
; DI float acc_get_i(const acc_t* base, unsigned idx, float inv_scale) { return (float)(*(const acc_t*)((const char*)base + idx * 8u)) * inv_scale; }
; template <class T> DI T* boff(T* base, unsigned byte_off) { return (T*)((char*)base + byte_off); }
;     DI void operator()(const f32x4 (&acc)[2][2][4][2], const Unit& u, int wr, int wc, int fr, int fq) const {
;     ...
;                 for (int m = 0; m < 4; ++m) { const int row = u.pm * BM + ai * HALF + wr * 64 + m * 16 + fr;
;                     const float rs = rstd_of(acc_get_i(ssq, (unsigned)row, 1.0f / SSQ_SCALE), 1.0f / DM);
;                     const f32x4 g = acc[ai][0][m][n] * rs, up = acc[ai][1][m][n] * rs;
;                     f32x4 a;
; #pragma unroll
;                     for (int j = 0; j < 4; ++j) { const float s1 = __shfl(fr == 15 ? pg[j] : g[j], src1), s2 = __shfl(fr >= 14 ? pg[j] : g[j], src2);
;                         a[j] = silu_f(cbv[j] + w0[j] * s2 + w1[j] * s1 + w2[j] * g[j]) * up[j]; }
;                     u32x2 gw; gw.x = pk2(g[0], g[1]); gw.y = pk2(g[2], g[3]);
;                     if (m == 0 && fr < 2) {
;                         *boff((u32x2*)GS, (unsigned)(((row >> 6) * 4 + 2 + fr) * DFF + c4) * 2u) = gw;
;                         u32x2 uw; uw.x = pk2(up[0], up[1]); uw.y = pk2(up[2], up[3]); *boff((u32x2*)US, (unsigned)(((row >> 6) * 2 + fr) * DFF + c4) * 2u) = uw;
;                     } else { u32x2 w; w.x = pk2(a[0], a[1]); w.y = pk2(a[2], a[3]); *boff((u32x2*)A2, (unsigned)(row * DFF + c4) * 2u) = w; }
;                     if (m == 3 && fr >= 14) {
;                         *boff((u32x2*)GS, (unsigned)(((row >> 6) * 4 + (fr - 14)) * DFF + c4) * 2u) = gw;
;                         if ((row & (SEQ - 1)) >= SEQ - 2) *boff((f32x4*)fcp, (unsigned)(((row >> 11) * 2 + ((row & (SEQ - 1)) - (SEQ - 2))) * DFF + c4) * 4u) = g;
;                     }
.LBB0_3100:
	s_or_b64 exec, exec, s[0:1]
	s_addk_i32 s15, 0x80
	v_or_b32_e32 v185, s15, v209
	v_lshlrev_b32_e32 v188, 3, v185
	v_mul_lo_u32 v231, v185, s90
	v_mov_b32_e32 v148, v240
	v_pk_mul_f32 v[194:195], v[60:61], v[148:149] op_sel_hi:[1,0]
	v_pk_mul_f32 v[192:193], v[62:63], v[148:149] op_sel_hi:[1,0]
	v_mov_b32_e32 v190, 0
	v_mov_b32_dpp v190, v194 row_shr:1 row_mask:0xf bank_mask:0xf
	v_mov_b32_e32 v198, 0
	v_mov_b32_dpp v198, v194 row_shr:2 row_mask:0xf bank_mask:0xf
	v_mov_b32_e32 v191, 0
	v_mov_b32_dpp v191, v195 row_shr:1 row_mask:0xf bank_mask:0xf
	v_mov_b32_e32 v199, 0
	v_mov_b32_dpp v199, v195 row_shr:2 row_mask:0xf bank_mask:0xf
	v_mov_b32_e32 v196, 0
	v_mov_b32_dpp v196, v192 row_shr:1 row_mask:0xf bank_mask:0xf
	v_mov_b32_e32 v200, 0
	v_mov_b32_dpp v200, v192 row_shr:2 row_mask:0xf bank_mask:0xf
	v_mov_b32_e32 v197, 0
	v_mov_b32_dpp v197, v193 row_shr:1 row_mask:0xf bank_mask:0xf
	v_mov_b32_e32 v201, 0
	v_mov_b32_dpp v201, v193 row_shr:2 row_mask:0xf bank_mask:0xf
	v_pk_mul_f32 v[146:147], v[54:55], v[148:149] op_sel_hi:[1,0]
	v_pk_mul_f32 v[148:149], v[52:53], v[148:149] op_sel_hi:[1,0]
	s_and_saveexec_b64 s[0:1], s[40:41]
	s_xor_b64 s[0:1], exec, s[0:1]
	s_cbranch_execz .LBB0_3102
	v_pk_fma_f32 v[150:151], v[130:131], v[198:199], v[142:143]
	s_nop 0
	v_pk_fma_f32 v[150:151], v[134:135], v[190:191], v[150:151]
	v_pk_fma_f32 v[190:191], v[132:133], v[200:201], v[144:145]
	v_pk_fma_f32 v[150:151], v[138:139], v[194:195], v[150:151]
	v_pk_fma_f32 v[190:191], v[136:137], v[196:197], v[190:191]
	v_mul_f32_e32 v152, 0xbfb8aa3b, v150
	v_mul_f32_e32 v153, 0xbfb8aa3b, v151
	v_pk_fma_f32 v[190:191], v[140:141], v[192:193], v[190:191]
	v_exp_f32_e32 v152, v152
	v_exp_f32_e32 v153, v153
	v_mul_f32_e32 v196, 0xbfb8aa3b, v190
	v_mul_f32_e32 v197, 0xbfb8aa3b, v191
	v_exp_f32_e32 v196, v196
	v_exp_f32_e32 v197, v197
	v_add_f32_e32 v152, 1.0, v152
	v_add_f32_e32 v153, 1.0, v153
	v_rcp_f32_e32 v152, v152
	v_rcp_f32_e32 v153, v153
	v_add_f32_e32 v196, 1.0, v196
	v_add_f32_e32 v197, 1.0, v197
	v_rcp_f32_e32 v196, v196
	v_rcp_f32_e32 v197, v197
	v_pk_mul_f32 v[150:151], v[150:151], v[152:153]
	s_nop 0
	v_pk_mul_f32 v[148:149], v[148:149], v[150:151]
	v_pk_mul_f32 v[150:151], v[190:191], v[196:197]
	v_cvt_pk_bf16_f32 v148, v148, v149
	v_pk_mul_f32 v[146:147], v[146:147], v[150:151]
	s_nop 0
	v_cvt_pk_bf16_f32 v149, v146, v147
	v_add_lshl_u32 v146, v231, v176, 1
	global_store_dwordx2 v146, v[148:149], s[46:47]
.LBB0_3102:
	s_or_saveexec_b64 s[0:1], s[0:1]
	s_ashr_i32 s2, s15, 4
	v_add_u32_e32 v150, s2, v209
	s_lshr_b32 s3, s15, 5
	v_mul_lo_u32 v191, v150, s90
	v_add_u32_e32 v150, s3, v209
	v_mul_lo_u32 v232, v150, s90
	s_xor_b64 exec, exec, s[0:1]
	s_cbranch_execz .LBB0_3104
	v_cvt_pk_bf16_f32 v150, v194, v195
	v_cvt_pk_bf16_f32 v151, v192, v193
	v_add_lshl_u32 v152, v232, v176, 1
	v_add_lshl_u32 v153, v191, v202, 1
	v_cvt_pk_bf16_f32 v148, v148, v149
	v_cvt_pk_bf16_f32 v149, v146, v147
	global_store_dwordx2 v153, v[150:151], s[50:51]
	global_store_dwordx2 v152, v[148:149], s[52:53]
.LBB0_3104:
	s_or_b64 exec, exec, s[0:1]
	v_or_b32_e32 v200, 16, v185
	v_add_u32_e32 v146, s2, v212
	v_lshlrev_b32_e32 v190, 3, v200
	v_mul_lo_u32 v221, v146, s90
	s_ashr_i32 s0, s15, 10
	s_and_b32 s15, s0, 0x3ffffffe
	s_add_i32 s15, s15, 0x3ffff802
	v_mov_b32_e32 v150, v241
	v_pk_mul_f32 v[148:149], v[44:45], v[150:151] op_sel_hi:[1,0]
	v_pk_mul_f32 v[146:147], v[46:47], v[150:151] op_sel_hi:[1,0]
	v_mov_b32_dpp v152, v194 row_ror:1 row_mask:0xf bank_mask:0xf
	v_mov_b32_dpp v152, v148 row_shr:1 row_mask:0xf bank_mask:0xf
	v_mov_b32_dpp v194, v194 row_ror:2 row_mask:0xf bank_mask:0xf
	v_mov_b32_dpp v194, v148 row_shr:2 row_mask:0xf bank_mask:0xf
	v_mov_b32_dpp v153, v195 row_ror:1 row_mask:0xf bank_mask:0xf
	v_mov_b32_dpp v153, v149 row_shr:1 row_mask:0xf bank_mask:0xf
	v_mov_b32_dpp v195, v195 row_ror:2 row_mask:0xf bank_mask:0xf
	v_mov_b32_dpp v195, v149 row_shr:2 row_mask:0xf bank_mask:0xf
	v_mov_b32_dpp v196, v192 row_ror:1 row_mask:0xf bank_mask:0xf
	v_mov_b32_dpp v196, v146 row_shr:1 row_mask:0xf bank_mask:0xf
	v_mov_b32_dpp v192, v192 row_ror:2 row_mask:0xf bank_mask:0xf
	v_mov_b32_dpp v192, v146 row_shr:2 row_mask:0xf bank_mask:0xf
	v_pk_fma_f32 v[194:195], v[130:131], v[194:195], v[142:143]
	v_mov_b32_dpp v197, v193 row_ror:1 row_mask:0xf bank_mask:0xf
	v_mov_b32_dpp v197, v147 row_shr:1 row_mask:0xf bank_mask:0xf
	v_pk_fma_f32 v[152:153], v[134:135], v[152:153], v[194:195]
	v_pk_fma_f32 v[152:153], v[138:139], v[148:149], v[152:153]
	v_mov_b32_dpp v193, v193 row_ror:2 row_mask:0xf bank_mask:0xf
	v_mov_b32_dpp v193, v147 row_shr:2 row_mask:0xf bank_mask:0xf
	v_mul_f32_e32 v194, 0xbfb8aa3b, v152
	v_mul_f32_e32 v195, 0xbfb8aa3b, v153
	v_exp_f32_e32 v194, v194
	v_exp_f32_e32 v195, v195
	v_pk_mul_f32 v[198:199], v[38:39], v[150:151] op_sel_hi:[1,0]
	v_add_f32_e32 v194, 1.0, v194
	v_add_f32_e32 v195, 1.0, v195
	v_rcp_f32_e32 v194, v194
	v_rcp_f32_e32 v195, v195
	v_pk_mul_f32 v[150:151], v[36:37], v[150:151] op_sel_hi:[1,0]
	v_pk_mul_f32 v[152:153], v[152:153], v[194:195]
	s_nop 0
	v_pk_mul_f32 v[150:151], v[150:151], v[152:153]
	v_pk_fma_f32 v[152:153], v[132:133], v[192:193], v[144:145]
	v_mul_lo_u32 v195, v200, s90
	v_pk_fma_f32 v[152:153], v[136:137], v[196:197], v[152:153]
	v_cvt_pk_bf16_f32 v150, v150, v151
	v_pk_fma_f32 v[152:153], v[140:141], v[146:147], v[152:153]
	v_add_u32_e32 v233, 0xb000, v195
	v_mul_f32_e32 v192, 0xbfb8aa3b, v152
	v_mul_f32_e32 v193, 0xbfb8aa3b, v153
	v_exp_f32_e32 v192, v192
	v_exp_f32_e32 v193, v193
	v_add_u32_e32 v234, 0x16000, v195
	v_add_f32_e32 v192, 1.0, v192
	v_add_f32_e32 v193, 1.0, v193
	v_rcp_f32_e32 v192, v192
; DI unsigned pk2(float lo, float hi) { f32x2 v = {lo, hi}; bf16x2_t b = __builtin_convertvector(v, bf16x2_t); return __builtin_bit_cast(unsigned, b); }
; DI float silu_f(float x) { return x * __builtin_amdgcn_rcpf(1.f + __builtin_amdgcn_exp2f(-LOG2E * x)); }
; DI float rstd_of(float ssq, float inv_n) { return 1.0f / sqrtf(ssq * inv_n + EPS); }
; DI float acc_get_i(const acc_t* base, unsigned idx, float inv_scale) { return (float)(*(const acc_t*)((const char*)base + idx * 8u)) * inv_scale; }
; template <class T> DI T* boff(T* base, unsigned byte_off) { return (T*)((char*)base + byte_off); }
;     DI void operator()(const f32x4 (&acc)[2][2][4][2], const Unit& u, int wr, int wc, int fr, int fq) const {
;     ...
;                 for (int m = 0; m < 4; ++m) { const int row = u.pm * BM + ai * HALF + wr * 64 + m * 16 + fr;
;                     const float rs = rstd_of(acc_get_i(ssq, (unsigned)row, 1.0f / SSQ_SCALE), 1.0f / DM);
;                     const f32x4 g = acc[ai][0][m][n] * rs, up = acc[ai][1][m][n] * rs;
;                     f32x4 a;
; #pragma unroll
;                     for (int j = 0; j < 4; ++j) { const float s1 = __shfl(fr == 15 ? pg[j] : g[j], src1), s2 = __shfl(fr >= 14 ? pg[j] : g[j], src2);
;                         a[j] = silu_f(cbv[j] + w0[j] * s2 + w1[j] * s1 + w2[j] * g[j]) * up[j]; }
;                     u32x2 gw; gw.x = pk2(g[0], g[1]); gw.y = pk2(g[2], g[3]);
;                     if (m == 0 && fr < 2) {
;                         *boff((u32x2*)GS, (unsigned)(((row >> 6) * 4 + 2 + fr) * DFF + c4) * 2u) = gw;
;                         u32x2 uw; uw.x = pk2(up[0], up[1]); uw.y = pk2(up[2], up[3]); *boff((u32x2*)US, (unsigned)(((row >> 6) * 2 + fr) * DFF + c4) * 2u) = uw;
;                     } else { u32x2 w; w.x = pk2(a[0], a[1]); w.y = pk2(a[2], a[3]); *boff((u32x2*)A2, (unsigned)(row * DFF + c4) * 2u) = w; }
;                     if (m == 3 && fr >= 14) {
;                         *boff((u32x2*)GS, (unsigned)(((row >> 6) * 4 + (fr - 14)) * DFF + c4) * 2u) = gw;
;                         if ((row & (SEQ - 1)) >= SEQ - 2) *boff((f32x4*)fcp, (unsigned)(((row >> 11) * 2 + ((row & (SEQ - 1)) - (SEQ - 2))) * DFF + c4) * 4u) = g;
;                     }
	v_rcp_f32_e32 v193, v193
	s_nop 0
	v_pk_mul_f32 v[152:153], v[152:153], v[192:193]
	s_nop 0
	v_pk_mul_f32 v[152:153], v[198:199], v[152:153]
	v_lshl_or_b32 v192, v185, 3, v229
	v_cvt_pk_bf16_f32 v151, v152, v153
	v_add_lshl_u32 v152, v195, v176, 1
	global_store_dwordx2 v152, v[150:151], s[46:47]
	v_or_b32_e32 v185, 48, v185
	v_and_b32_e32 v235, 0x7ff, v185
	v_mov_b32_e32 v150, v242
	v_pk_mul_f32 v[198:199], v[28:29], v[150:151] op_sel_hi:[1,0]
	v_pk_mul_f32 v[196:197], v[30:31], v[150:151] op_sel_hi:[1,0]
	v_mov_b32_dpp v152, v148 row_ror:1 row_mask:0xf bank_mask:0xf
	v_mov_b32_dpp v152, v198 row_shr:1 row_mask:0xf bank_mask:0xf
	v_mov_b32_dpp v148, v148 row_ror:2 row_mask:0xf bank_mask:0xf
	v_mov_b32_dpp v148, v198 row_shr:2 row_mask:0xf bank_mask:0xf
	v_mov_b32_dpp v153, v149 row_ror:1 row_mask:0xf bank_mask:0xf
	v_mov_b32_dpp v153, v199 row_shr:1 row_mask:0xf bank_mask:0xf
	v_mov_b32_dpp v200, v146 row_ror:1 row_mask:0xf bank_mask:0xf
	v_mov_b32_dpp v200, v196 row_shr:1 row_mask:0xf bank_mask:0xf
	v_mov_b32_dpp v146, v146 row_ror:2 row_mask:0xf bank_mask:0xf
	v_mov_b32_dpp v146, v196 row_shr:2 row_mask:0xf bank_mask:0xf
	v_mov_b32_dpp v149, v149 row_ror:2 row_mask:0xf bank_mask:0xf
	v_mov_b32_dpp v149, v199 row_shr:2 row_mask:0xf bank_mask:0xf
	v_pk_fma_f32 v[148:149], v[130:131], v[148:149], v[142:143]
	v_mov_b32_dpp v201, v147 row_ror:1 row_mask:0xf bank_mask:0xf
	v_mov_b32_dpp v201, v197 row_shr:1 row_mask:0xf bank_mask:0xf
	v_pk_fma_f32 v[148:149], v[134:135], v[152:153], v[148:149]
	v_mov_b32_dpp v147, v147 row_ror:2 row_mask:0xf bank_mask:0xf
	v_mov_b32_dpp v147, v197 row_shr:2 row_mask:0xf bank_mask:0xf
	v_pk_fma_f32 v[148:149], v[138:139], v[198:199], v[148:149]
	v_mul_f32_e32 v152, 0xbfb8aa3b, v148
	v_mul_f32_e32 v153, 0xbfb8aa3b, v149
	v_exp_f32_e32 v152, v152
	v_exp_f32_e32 v153, v153
	v_add_f32_e32 v152, 1.0, v152
	v_add_f32_e32 v153, 1.0, v153
	v_rcp_f32_e32 v152, v152
	v_rcp_f32_e32 v153, v153
	v_pk_fma_f32 v[146:147], v[132:133], v[146:147], v[144:145]
	v_pk_mul_f32 v[202:203], v[22:23], v[150:151] op_sel_hi:[1,0]
	v_pk_fma_f32 v[146:147], v[136:137], v[200:201], v[146:147]
	v_pk_mul_f32 v[150:151], v[20:21], v[150:151] op_sel_hi:[1,0]
	v_pk_mul_f32 v[148:149], v[148:149], v[152:153]
	v_pk_fma_f32 v[146:147], v[140:141], v[196:197], v[146:147]
	v_pk_mul_f32 v[148:149], v[150:151], v[148:149]
	v_mul_f32_e32 v150, 0xbfb8aa3b, v146
	v_mul_f32_e32 v151, 0xbfb8aa3b, v147
	v_exp_f32_e32 v150, v150
	v_exp_f32_e32 v151, v151
	v_cvt_pk_bf16_f32 v148, v148, v149
	v_lshlrev_b32_e32 v194, 3, v185
	v_add_f32_e32 v150, 1.0, v150
	v_add_f32_e32 v151, 1.0, v151
	v_rcp_f32_e32 v150, v150
	v_rcp_f32_e32 v151, v151
	s_nop 0
	v_pk_mul_f32 v[146:147], v[146:147], v[150:151]
	s_nop 0
	v_pk_mul_f32 v[146:147], v[202:203], v[146:147]
	s_nop 0
	v_cvt_pk_bf16_f32 v149, v146, v147
	v_add_lshl_u32 v146, v233, v176, 1
	global_store_dwordx2 v146, v[148:149], s[46:47]
	v_mov_b32_e32 v150, v243
	v_pk_mul_f32 v[146:147], v[12:13], v[150:151] op_sel_hi:[1,0]
	v_pk_mul_f32 v[148:149], v[14:15], v[150:151] op_sel_hi:[1,0]
	v_mov_b32_dpp v152, v198 row_ror:1 row_mask:0xf bank_mask:0xf
	v_mov_b32_dpp v152, v146 row_shr:1 row_mask:0xf bank_mask:0xf
	v_mov_b32_dpp v198, v198 row_ror:2 row_mask:0xf bank_mask:0xf
	v_mov_b32_dpp v198, v146 row_shr:2 row_mask:0xf bank_mask:0xf
	v_mov_b32_dpp v153, v199 row_ror:1 row_mask:0xf bank_mask:0xf
	v_mov_b32_dpp v153, v147 row_shr:1 row_mask:0xf bank_mask:0xf
	v_mov_b32_dpp v199, v199 row_ror:2 row_mask:0xf bank_mask:0xf
	v_mov_b32_dpp v199, v147 row_shr:2 row_mask:0xf bank_mask:0xf
	v_mov_b32_dpp v200, v196 row_ror:1 row_mask:0xf bank_mask:0xf
	v_mov_b32_dpp v200, v148 row_shr:1 row_mask:0xf bank_mask:0xf
	v_mov_b32_dpp v196, v196 row_ror:2 row_mask:0xf bank_mask:0xf
	v_mov_b32_dpp v196, v148 row_shr:2 row_mask:0xf bank_mask:0xf
	v_pk_fma_f32 v[130:131], v[130:131], v[198:199], v[142:143]
	v_mov_b32_dpp v201, v197 row_ror:1 row_mask:0xf bank_mask:0xf
	v_mov_b32_dpp v201, v149 row_shr:1 row_mask:0xf bank_mask:0xf
	v_pk_fma_f32 v[130:131], v[134:135], v[152:153], v[130:131]
	v_pk_fma_f32 v[130:131], v[138:139], v[146:147], v[130:131]
	v_mov_b32_dpp v197, v197 row_ror:2 row_mask:0xf bank_mask:0xf
	v_mov_b32_dpp v197, v149 row_shr:2 row_mask:0xf bank_mask:0xf
	v_mul_f32_e32 v134, 0xbfb8aa3b, v130
	v_mul_f32_e32 v135, 0xbfb8aa3b, v131
	v_exp_f32_e32 v134, v134
	v_exp_f32_e32 v135, v135
	v_pk_mul_f32 v[202:203], v[6:7], v[150:151] op_sel_hi:[1,0]
	v_add_f32_e32 v134, 1.0, v134
	v_add_f32_e32 v135, 1.0, v135
	v_rcp_f32_e32 v134, v134
	v_rcp_f32_e32 v135, v135
	v_pk_fma_f32 v[132:133], v[132:133], v[196:197], v[144:145]
	v_pk_mul_f32 v[150:151], v[4:5], v[150:151] op_sel_hi:[1,0]
	v_pk_fma_f32 v[132:133], v[136:137], v[200:201], v[132:133]
	v_pk_mul_f32 v[130:131], v[130:131], v[134:135]
	v_pk_fma_f32 v[132:133], v[140:141], v[148:149], v[132:133]
	v_pk_mul_f32 v[130:131], v[150:151], v[130:131]
	v_mul_f32_e32 v134, 0xbfb8aa3b, v132
	v_mul_f32_e32 v135, 0xbfb8aa3b, v133
	v_exp_f32_e32 v134, v134
	v_exp_f32_e32 v135, v135
	v_cvt_pk_bf16_f32 v130, v130, v131
	v_add_f32_e32 v134, 1.0, v134
	v_add_f32_e32 v135, 1.0, v135
	v_rcp_f32_e32 v134, v134
	v_rcp_f32_e32 v135, v135
	s_nop 0
	v_pk_mul_f32 v[132:133], v[132:133], v[134:135]
	s_nop 0
	v_pk_mul_f32 v[132:133], v[202:203], v[132:133]
	s_nop 0
	v_cvt_pk_bf16_f32 v131, v132, v133
	v_add_lshl_u32 v132, v234, v176, 1
	global_store_dwordx2 v132, v[130:131], s[46:47]
	s_and_saveexec_b64 s[0:1], s[38:39]
	s_cbranch_execz .LBB0_3107
	s_movk_i32 s2, 0x7fd
	v_add_lshl_u32 v132, v221, v176, 1
	v_cvt_pk_bf16_f32 v130, v146, v147
	v_cvt_pk_bf16_f32 v131, v148, v149
	v_cmp_lt_u32_e32 vcc, s2, v235
	global_store_dwordx2 v132, v[130:131], s[50:51]
	s_and_b64 exec, exec, vcc
	s_cbranch_execz .LBB0_3107
	v_add_u32_e32 v130, s15, v235
	v_mul_lo_u32 v130, v130, s90
	v_add_lshl_u32 v130, v130, v176, 2
	global_store_dwordx4 v130, v[146:149], s[58:59]
; DI unsigned pk2(float lo, float hi) { f32x2 v = {lo, hi}; bf16x2_t b = __builtin_convertvector(v, bf16x2_t); return __builtin_bit_cast(unsigned, b); }
; DI float silu_f(float x) { return x * __builtin_amdgcn_rcpf(1.f + __builtin_amdgcn_exp2f(-LOG2E * x)); }
; DI float rstd_of(float ssq, float inv_n) { return 1.0f / sqrtf(ssq * inv_n + EPS); }
; DI float acc_get_i(const acc_t* base, unsigned idx, float inv_scale) { return (float)(*(const acc_t*)((const char*)base + idx * 8u)) * inv_scale; }
; template <class T> DI T* boff(T* base, unsigned byte_off) { return (T*)((char*)base + byte_off); }
;     DI void operator()(const f32x4 (&acc)[2][2][4][2], const Unit& u, int wr, int wc, int fr, int fq) const {
;     ...
;             const int c4 = c8 + 4 * n;
;             const f32x4 w0 = *(const f32x4*)(cw + c4), w1 = *(const f32x4*)(cw + DFF + c4), w2 = *(const f32x4*)(cw + 2 * DFF + c4), cbv = *(const f32x4*)(cb + c4);
; #pragma unroll
;             for (int ai = 0; ai < 2; ++ai) {
;                 f32x4 pg = {0.f, 0.f, 0.f, 0.f};
; #pragma unroll
;                 for (int m = 0; m < 4; ++m) { const int row = u.pm * BM + ai * HALF + wr * 64 + m * 16 + fr;
;                     const float rs = rstd_of(acc_get_i(ssq, (unsigned)row, 1.0f / SSQ_SCALE), 1.0f / DM);
;                     const f32x4 g = acc[ai][0][m][n] * rs, up = acc[ai][1][m][n] * rs;
;                     f32x4 a;
; #pragma unroll
;                     for (int j = 0; j < 4; ++j) { const float s1 = __shfl(fr == 15 ? pg[j] : g[j], src1), s2 = __shfl(fr >= 14 ? pg[j] : g[j], src2);
;                         a[j] = silu_f(cbv[j] + w0[j] * s2 + w1[j] * s1 + w2[j] * g[j]) * up[j]; }
;                     u32x2 gw; gw.x = pk2(g[0], g[1]); gw.y = pk2(g[2], g[3]);
;                     if (m == 0 && fr < 2) {
;                         *boff((u32x2*)GS, (unsigned)(((row >> 6) * 4 + 2 + fr) * DFF + c4) * 2u) = gw;
;                         u32x2 uw; uw.x = pk2(up[0], up[1]); uw.y = pk2(up[2], up[3]); *boff((u32x2*)US, (unsigned)(((row >> 6) * 2 + fr) * DFF + c4) * 2u) = uw;
;                     } else { u32x2 w; w.x = pk2(a[0], a[1]); w.y = pk2(a[2], a[3]); *boff((u32x2*)A2, (unsigned)(row * DFF + c4) * 2u) = w; }
.LBB0_3107:
	s_or_b64 exec, exec, s[0:1]
	v_or_b32_e32 v196, 4, v176
	v_ashrrev_i32_e32 v197, 31, v196
	v_lshlrev_b64 v[134:135], 2, v[196:197]
	v_lshl_add_u64 v[146:147], s[48:49], 0, v[96:97]
	v_lshl_add_u64 v[136:137], s[62:63], 0, v[134:135]
	v_lshl_add_u64 v[134:135], s[64:65], 0, v[134:135]
	global_load_dwordx4 v[130:133], v[178:179], off offset:16
	global_load_dwordx4 v[138:141], v[136:137], off
	s_nop 0
	global_load_dwordx4 v[134:137], v[134:135], off
	s_nop 0
	global_load_dwordx4 v[142:145], v[180:181], off offset:16
	s_nop 0
	s_waitcnt vmcnt(0)
	v_mov_b32_e32 v96, v236
	v_pk_mul_f32 v[148:149], v[122:123], v[96:97] op_sel_hi:[1,0]
	v_pk_mul_f32 v[146:147], v[124:125], v[96:97] op_sel_hi:[1,0]
	v_pk_mul_f32 v[178:179], v[116:117], v[96:97] op_sel_hi:[1,0]
	v_pk_mul_f32 v[180:181], v[114:115], v[96:97] op_sel_hi:[1,0]
	v_mov_b32_e32 v200, 0
	v_mov_b32_dpp v200, v148 row_shr:1 row_mask:0xf bank_mask:0xf
	v_mov_b32_e32 v204, 0
	v_mov_b32_dpp v204, v148 row_shr:2 row_mask:0xf bank_mask:0xf
	v_mov_b32_e32 v201, 0
	v_mov_b32_dpp v201, v149 row_shr:1 row_mask:0xf bank_mask:0xf
	v_mov_b32_e32 v205, 0
	v_mov_b32_dpp v205, v149 row_shr:2 row_mask:0xf bank_mask:0xf
	v_mov_b32_e32 v198, 0
	v_mov_b32_dpp v198, v146 row_shr:1 row_mask:0xf bank_mask:0xf
	v_mov_b32_e32 v202, 0
	v_mov_b32_dpp v202, v146 row_shr:2 row_mask:0xf bank_mask:0xf
	v_mov_b32_e32 v199, 0
	v_mov_b32_dpp v199, v147 row_shr:1 row_mask:0xf bank_mask:0xf
	v_mov_b32_e32 v203, 0
	v_mov_b32_dpp v203, v147 row_shr:2 row_mask:0xf bank_mask:0xf
	s_and_saveexec_b64 s[0:1], s[40:41]
	s_xor_b64 s[0:1], exec, s[0:1]
	s_cbranch_execz .LBB0_3109
	v_pk_fma_f32 v[150:151], v[130:131], v[204:205], v[142:143]
	s_nop 0
	v_pk_fma_f32 v[150:151], v[138:139], v[200:201], v[150:151]
	v_pk_fma_f32 v[200:201], v[132:133], v[202:203], v[144:145]
	v_pk_fma_f32 v[150:151], v[134:135], v[148:149], v[150:151]
	v_pk_fma_f32 v[198:199], v[140:141], v[198:199], v[200:201]
	v_mul_f32_e32 v96, 0xbfb8aa3b, v150
	v_exp_f32_e32 v96, v96
	v_mul_f32_e32 v152, 0xbfb8aa3b, v151
	v_exp_f32_e32 v152, v152
	v_pk_fma_f32 v[198:199], v[136:137], v[146:147], v[198:199]
	v_add_f32_e32 v96, 1.0, v96
	v_mul_f32_e32 v183, 0xbfb8aa3b, v199
	v_add_f32_e32 v153, 1.0, v152
	v_rcp_f32_e32 v152, v96
	v_mul_f32_e32 v96, 0xbfb8aa3b, v198
	v_exp_f32_e32 v96, v96
	v_exp_f32_e32 v183, v183
	v_rcp_f32_e32 v153, v153
	v_add_f32_e32 v96, 1.0, v96
	v_rcp_f32_e32 v200, v96
	v_add_f32_e32 v96, 1.0, v183
	v_rcp_f32_e32 v201, v96
	v_pk_mul_f32 v[150:151], v[150:151], v[152:153]
	v_add_lshl_u32 v96, v218, v196, 1
	v_pk_mul_f32 v[150:151], v[180:181], v[150:151]
	v_pk_mul_f32 v[152:153], v[198:199], v[200:201]
	v_cvt_pk_bf16_f32 v150, v150, v151
	v_pk_mul_f32 v[152:153], v[178:179], v[152:153]
	s_nop 0
	v_cvt_pk_bf16_f32 v151, v152, v153
	global_store_dwordx2 v96, v[150:151], s[46:47]

; DI unsigned pk2(float lo, float hi) { f32x2 v = {lo, hi}; bf16x2_t b = __builtin_convertvector(v, bf16x2_t); return __builtin_bit_cast(unsigned, b); }
; DI float silu_f(float x) { return x * __builtin_amdgcn_rcpf(1.f + __builtin_amdgcn_exp2f(-LOG2E * x)); }
; DI float rstd_of(float ssq, float inv_n) { return 1.0f / sqrtf(ssq * inv_n + EPS); }
; DI float acc_get_i(const acc_t* base, unsigned idx, float inv_scale) { return (float)(*(const acc_t*)((const char*)base + idx * 8u)) * inv_scale; }
; template <class T> DI T* boff(T* base, unsigned byte_off) { return (T*)((char*)base + byte_off); }
;     DI void operator()(const f32x4 (&acc)[2][2][4][2], const Unit& u, int wr, int wc, int fr, int fq) const {
;     ...
;                 for (int m = 0; m < 4; ++m) { const int row = u.pm * BM + ai * HALF + wr * 64 + m * 16 + fr;
;                     const float rs = rstd_of(acc_get_i(ssq, (unsigned)row, 1.0f / SSQ_SCALE), 1.0f / DM);
;                     const f32x4 g = acc[ai][0][m][n] * rs, up = acc[ai][1][m][n] * rs;
;                     f32x4 a;
; #pragma unroll
;                     for (int j = 0; j < 4; ++j) { const float s1 = __shfl(fr == 15 ? pg[j] : g[j], src1), s2 = __shfl(fr >= 14 ? pg[j] : g[j], src2);
;                         a[j] = silu_f(cbv[j] + w0[j] * s2 + w1[j] * s1 + w2[j] * g[j]) * up[j]; }
;                     u32x2 gw; gw.x = pk2(g[0], g[1]); gw.y = pk2(g[2], g[3]);
;                     if (m == 0 && fr < 2) {
;                         *boff((u32x2*)GS, (unsigned)(((row >> 6) * 4 + 2 + fr) * DFF + c4) * 2u) = gw;
;                         u32x2 uw; uw.x = pk2(up[0], up[1]); uw.y = pk2(up[2], up[3]); *boff((u32x2*)US, (unsigned)(((row >> 6) * 2 + fr) * DFF + c4) * 2u) = uw;
;                     } else { u32x2 w; w.x = pk2(a[0], a[1]); w.y = pk2(a[2], a[3]); *boff((u32x2*)A2, (unsigned)(row * DFF + c4) * 2u) = w; }
;                     if (m == 3 && fr >= 14) {
;                         *boff((u32x2*)GS, (unsigned)(((row >> 6) * 4 + (fr - 14)) * DFF + c4) * 2u) = gw;
;                         if ((row & (SEQ - 1)) >= SEQ - 2) *boff((f32x4*)fcp, (unsigned)(((row >> 11) * 2 + ((row & (SEQ - 1)) - (SEQ - 2))) * DFF + c4) * 4u) = g;
;                     }
.LBB0_3111:
	s_or_b64 exec, exec, s[0:1]
	v_mov_b32_e32 v183, v97
	v_lshl_add_u64 v[150:151], s[48:49], 0, v[182:183]
	v_add_lshl_u32 v187, v187, v196, 1
	v_mov_b32_e32 v185, v97
	v_lshl_add_u64 v[184:185], s[48:49], 0, v[184:185]
	v_mov_b32_e32 v150, v237
	v_pk_mul_f32 v[152:153], v[108:109], v[150:151] op_sel_hi:[1,0]
	v_pk_mul_f32 v[178:179], v[106:107], v[150:151] op_sel_hi:[1,0]
	v_mov_b32_dpp v180, v146 row_ror:2 row_mask:0xf bank_mask:0xf
	v_mov_b32_dpp v180, v152 row_shr:2 row_mask:0xf bank_mask:0xf
	v_mov_b32_dpp v181, v147 row_ror:2 row_mask:0xf bank_mask:0xf
	v_mov_b32_dpp v181, v153 row_shr:2 row_mask:0xf bank_mask:0xf
	v_mov_b32_dpp v182, v146 row_ror:1 row_mask:0xf bank_mask:0xf
	v_mov_b32_dpp v182, v152 row_shr:1 row_mask:0xf bank_mask:0xf
	v_mov_b32_dpp v183, v147 row_ror:1 row_mask:0xf bank_mask:0xf
	v_mov_b32_dpp v183, v153 row_shr:1 row_mask:0xf bank_mask:0xf
	v_mov_b32_dpp v147, v149 row_ror:1 row_mask:0xf bank_mask:0xf
	v_mov_b32_dpp v147, v179 row_shr:1 row_mask:0xf bank_mask:0xf
	v_mov_b32_dpp v149, v149 row_ror:2 row_mask:0xf bank_mask:0xf
	v_mov_b32_dpp v149, v179 row_shr:2 row_mask:0xf bank_mask:0xf
	v_mov_b32_dpp v146, v148 row_ror:1 row_mask:0xf bank_mask:0xf
	v_mov_b32_dpp v146, v178 row_shr:1 row_mask:0xf bank_mask:0xf
	v_mov_b32_dpp v148, v148 row_ror:2 row_mask:0xf bank_mask:0xf
	v_mov_b32_dpp v148, v178 row_shr:2 row_mask:0xf bank_mask:0xf
	v_pk_fma_f32 v[148:149], v[130:131], v[148:149], v[142:143]
	v_pk_fma_f32 v[180:181], v[132:133], v[180:181], v[144:145]
	v_pk_fma_f32 v[146:147], v[138:139], v[146:147], v[148:149]
	v_pk_fma_f32 v[148:149], v[140:141], v[182:183], v[180:181]
	v_pk_fma_f32 v[146:147], v[134:135], v[178:179], v[146:147]
	v_pk_fma_f32 v[148:149], v[136:137], v[152:153], v[148:149]
	v_mul_f32_e32 v151, 0xbfb8aa3b, v146
	v_mul_f32_e32 v180, 0xbfb8aa3b, v147
	v_mul_f32_e32 v181, 0xbfb8aa3b, v148
	v_mul_f32_e32 v182, 0xbfb8aa3b, v149
	v_exp_f32_e32 v151, v151
	v_exp_f32_e32 v180, v180
	v_exp_f32_e32 v181, v181
	v_exp_f32_e32 v182, v182
	v_add_f32_e32 v151, 1.0, v151
	v_add_f32_e32 v183, 1.0, v180
	v_add_f32_e32 v193, 1.0, v181
	v_add_f32_e32 v197, 1.0, v182
	v_rcp_f32_e32 v180, v151
	v_rcp_f32_e32 v181, v183
	v_rcp_f32_e32 v182, v193
	v_rcp_f32_e32 v183, v197
	v_pk_mul_f32 v[198:199], v[100:101], v[150:151] op_sel_hi:[1,0]
	v_pk_mul_f32 v[150:151], v[98:99], v[150:151] op_sel_hi:[1,0]
	v_pk_mul_f32 v[146:147], v[146:147], v[180:181]
	v_pk_mul_f32 v[148:149], v[148:149], v[182:183]
	v_pk_mul_f32 v[146:147], v[150:151], v[146:147]
	v_pk_mul_f32 v[148:149], v[198:199], v[148:149]
	v_cvt_pk_bf16_f32 v146, v146, v147
	v_cvt_pk_bf16_f32 v147, v148, v149
	global_store_dwordx2 v187, v[146:147], s[46:47]
	v_mov_b32_e32 v187, v97
	v_add_lshl_u32 v193, v220, v196, 1
	v_mov_b32_e32 v146, v238
	v_pk_mul_f32 v[150:151], v[90:91], v[146:147] op_sel_hi:[1,0]
	v_pk_mul_f32 v[180:181], v[88:89], v[146:147] op_sel_hi:[1,0]
	v_mov_b32_dpp v149, v179 row_ror:1 row_mask:0xf bank_mask:0xf
	s_nop 0
	v_mov_b32_dpp v149, v181 row_shr:1 row_mask:0xf bank_mask:0xf
	v_mov_b32_dpp v148, v178 row_ror:1 row_mask:0xf bank_mask:0xf
	v_mov_b32_dpp v148, v180 row_shr:1 row_mask:0xf bank_mask:0xf
	v_mov_b32_dpp v182, v152 row_ror:1 row_mask:0xf bank_mask:0xf
	v_mov_b32_dpp v182, v150 row_shr:1 row_mask:0xf bank_mask:0xf
	v_mov_b32_dpp v183, v153 row_ror:1 row_mask:0xf bank_mask:0xf
	v_mov_b32_dpp v183, v151 row_shr:1 row_mask:0xf bank_mask:0xf
	v_mov_b32_dpp v246, v178 row_ror:2 row_mask:0xf bank_mask:0xf
	v_mov_b32_dpp v246, v180 row_shr:2 row_mask:0xf bank_mask:0xf
	v_mov_b32_dpp v178, v152 row_ror:2 row_mask:0xf bank_mask:0xf
	v_mov_b32_dpp v178, v150 row_shr:2 row_mask:0xf bank_mask:0xf
	v_mov_b32_e32 v152, v246
	v_mov_b32_dpp v247, v179 row_ror:2 row_mask:0xf bank_mask:0xf
	v_mov_b32_dpp v247, v181 row_shr:2 row_mask:0xf bank_mask:0xf
	v_mov_b32_dpp v179, v153 row_ror:2 row_mask:0xf bank_mask:0xf
	v_mov_b32_dpp v179, v151 row_shr:2 row_mask:0xf bank_mask:0xf
	v_mov_b32_e32 v153, v247
	v_pk_fma_f32 v[152:153], v[130:131], v[152:153], v[142:143]
	v_pk_fma_f32 v[178:179], v[132:133], v[178:179], v[144:145]
	v_pk_fma_f32 v[148:149], v[138:139], v[148:149], v[152:153]
	v_lshl_add_u64 v[184:185], s[48:49], 0, v[186:187]
	v_pk_fma_f32 v[152:153], v[140:141], v[182:183], v[178:179]
	v_pk_fma_f32 v[148:149], v[134:135], v[180:181], v[148:149]
	v_pk_fma_f32 v[152:153], v[136:137], v[150:151], v[152:153]
	v_mul_f32_e32 v147, 0xbfb8aa3b, v148
	v_mul_f32_e32 v178, 0xbfb8aa3b, v149
	v_mul_f32_e32 v179, 0xbfb8aa3b, v152
	v_mul_f32_e32 v182, 0xbfb8aa3b, v153
	v_exp_f32_e32 v147, v147
	v_exp_f32_e32 v178, v178
	v_exp_f32_e32 v179, v179
	v_exp_f32_e32 v182, v182
	v_add_f32_e32 v147, 1.0, v147
	v_add_f32_e32 v183, 1.0, v178
	v_add_f32_e32 v186, 1.0, v179
	v_add_f32_e32 v187, 1.0, v182
	v_rcp_f32_e32 v178, v147
	v_rcp_f32_e32 v179, v183
	v_rcp_f32_e32 v182, v186
	v_rcp_f32_e32 v183, v187
	v_pk_mul_f32 v[186:187], v[82:83], v[146:147] op_sel_hi:[1,0]
	v_pk_mul_f32 v[146:147], v[80:81], v[146:147] op_sel_hi:[1,0]
	v_pk_mul_f32 v[148:149], v[148:149], v[178:179]
	v_pk_mul_f32 v[152:153], v[152:153], v[182:183]
	v_pk_mul_f32 v[146:147], v[146:147], v[148:149]
	v_pk_mul_f32 v[148:149], v[186:187], v[152:153]
	v_cvt_pk_bf16_f32 v146, v146, v147
	v_cvt_pk_bf16_f32 v147, v148, v149
	global_store_dwordx2 v193, v[146:147], s[46:47]
	v_mov_b32_e32 v152, v239
; DI unsigned pk2(float lo, float hi) { f32x2 v = {lo, hi}; bf16x2_t b = __builtin_convertvector(v, bf16x2_t); return __builtin_bit_cast(unsigned, b); }
; DI float silu_f(float x) { return x * __builtin_amdgcn_rcpf(1.f + __builtin_amdgcn_exp2f(-LOG2E * x)); }
; DI float rstd_of(float ssq, float inv_n) { return 1.0f / sqrtf(ssq * inv_n + EPS); }
; DI float acc_get_i(const acc_t* base, unsigned idx, float inv_scale) { return (float)(*(const acc_t*)((const char*)base + idx * 8u)) * inv_scale; }
; template <class T> DI T* boff(T* base, unsigned byte_off) { return (T*)((char*)base + byte_off); }
;     DI void operator()(const f32x4 (&acc)[2][2][4][2], const Unit& u, int wr, int wc, int fr, int fq) const {
;     ...
;                 for (int m = 0; m < 4; ++m) { const int row = u.pm * BM + ai * HALF + wr * 64 + m * 16 + fr;
;                     const float rs = rstd_of(acc_get_i(ssq, (unsigned)row, 1.0f / SSQ_SCALE), 1.0f / DM);
;                     const f32x4 g = acc[ai][0][m][n] * rs, up = acc[ai][1][m][n] * rs;
;                     f32x4 a;
; #pragma unroll
;                     for (int j = 0; j < 4; ++j) { const float s1 = __shfl(fr == 15 ? pg[j] : g[j], src1), s2 = __shfl(fr >= 14 ? pg[j] : g[j], src2);
;                         a[j] = silu_f(cbv[j] + w0[j] * s2 + w1[j] * s1 + w2[j] * g[j]) * up[j]; }
;                     u32x2 gw; gw.x = pk2(g[0], g[1]); gw.y = pk2(g[2], g[3]);
;                     if (m == 0 && fr < 2) {
;                         *boff((u32x2*)GS, (unsigned)(((row >> 6) * 4 + 2 + fr) * DFF + c4) * 2u) = gw;
;                         u32x2 uw; uw.x = pk2(up[0], up[1]); uw.y = pk2(up[2], up[3]); *boff((u32x2*)US, (unsigned)(((row >> 6) * 2 + fr) * DFF + c4) * 2u) = uw;
;                     } else { u32x2 w; w.x = pk2(a[0], a[1]); w.y = pk2(a[2], a[3]); *boff((u32x2*)A2, (unsigned)(row * DFF + c4) * 2u) = w; }
;                     if (m == 3 && fr >= 14) {
;                         *boff((u32x2*)GS, (unsigned)(((row >> 6) * 4 + (fr - 14)) * DFF + c4) * 2u) = gw;
;                         if ((row & (SEQ - 1)) >= SEQ - 2) *boff((f32x4*)fcp, (unsigned)(((row >> 11) * 2 + ((row & (SEQ - 1)) - (SEQ - 2))) * DFF + c4) * 4u) = g;
;                     }
	v_pk_mul_f32 v[148:149], v[74:75], v[152:153] op_sel_hi:[1,0]
	v_pk_mul_f32 v[146:147], v[72:73], v[152:153] op_sel_hi:[1,0]
	v_mov_b32_dpp v178, v180 row_ror:2 row_mask:0xf bank_mask:0xf
	s_nop 0
	v_mov_b32_dpp v178, v146 row_shr:2 row_mask:0xf bank_mask:0xf
	v_mov_b32_dpp v179, v181 row_ror:2 row_mask:0xf bank_mask:0xf
	v_mov_b32_dpp v179, v147 row_shr:2 row_mask:0xf bank_mask:0xf
	v_mov_b32_dpp v182, v150 row_ror:1 row_mask:0xf bank_mask:0xf
	v_mov_b32_dpp v182, v148 row_shr:1 row_mask:0xf bank_mask:0xf
	v_mov_b32_dpp v183, v151 row_ror:1 row_mask:0xf bank_mask:0xf
	v_mov_b32_dpp v183, v149 row_shr:1 row_mask:0xf bank_mask:0xf
	v_mov_b32_dpp v246, v181 row_ror:1 row_mask:0xf bank_mask:0xf
	v_mov_b32_dpp v246, v147 row_shr:1 row_mask:0xf bank_mask:0xf
	v_mov_b32_dpp v181, v151 row_ror:2 row_mask:0xf bank_mask:0xf
	v_mov_b32_dpp v181, v149 row_shr:2 row_mask:0xf bank_mask:0xf
	v_mov_b32_e32 v151, v246
	v_mov_b32_dpp v247, v150 row_ror:2 row_mask:0xf bank_mask:0xf
	v_mov_b32_dpp v247, v148 row_shr:2 row_mask:0xf bank_mask:0xf
	v_mov_b32_dpp v150, v180 row_ror:1 row_mask:0xf bank_mask:0xf
	v_mov_b32_dpp v150, v146 row_shr:1 row_mask:0xf bank_mask:0xf
	v_mov_b32_e32 v180, v247
	v_pk_fma_f32 v[178:179], v[130:131], v[178:179], v[142:143]
	v_pk_fma_f32 v[180:181], v[132:133], v[180:181], v[144:145]
	v_pk_fma_f32 v[150:151], v[138:139], v[150:151], v[178:179]
	v_pk_fma_f32 v[178:179], v[140:141], v[182:183], v[180:181]
	v_pk_fma_f32 v[150:151], v[134:135], v[146:147], v[150:151]
	v_pk_fma_f32 v[178:179], v[136:137], v[148:149], v[178:179]
	v_mul_f32_e32 v153, 0xbfb8aa3b, v150
	v_mul_f32_e32 v180, 0xbfb8aa3b, v151
	v_mul_f32_e32 v181, 0xbfb8aa3b, v178
	v_mul_f32_e32 v182, 0xbfb8aa3b, v179
	v_exp_f32_e32 v153, v153
	v_exp_f32_e32 v180, v180
	v_exp_f32_e32 v181, v181
	v_exp_f32_e32 v182, v182
	v_add_f32_e32 v153, 1.0, v153
	v_add_f32_e32 v183, 1.0, v180
	v_add_f32_e32 v184, 1.0, v181
	v_add_f32_e32 v185, 1.0, v182
	v_rcp_f32_e32 v180, v153
	v_rcp_f32_e32 v181, v183
	v_rcp_f32_e32 v182, v184
	v_rcp_f32_e32 v183, v185
	v_pk_mul_f32 v[184:185], v[66:67], v[152:153] op_sel_hi:[1,0]
	v_pk_mul_f32 v[152:153], v[64:65], v[152:153] op_sel_hi:[1,0]
	v_pk_mul_f32 v[150:151], v[150:151], v[180:181]
	v_pk_mul_f32 v[178:179], v[178:179], v[182:183]
	v_pk_mul_f32 v[150:151], v[152:153], v[150:151]
	v_pk_mul_f32 v[152:153], v[184:185], v[178:179]
	v_cvt_pk_bf16_f32 v150, v150, v151
	v_cvt_pk_bf16_f32 v151, v152, v153
	v_add_lshl_u32 v152, v230, v196, 1
	global_store_dwordx2 v152, v[150:151], s[46:47]
	s_and_saveexec_b64 s[0:1], s[38:39]
	s_cbranch_execz .LBB0_3114
	s_movk_i32 s2, 0x7fd
	v_add_lshl_u32 v152, v217, v196, 1
	v_cvt_pk_bf16_f32 v150, v146, v147
	v_cvt_pk_bf16_f32 v151, v148, v149
	v_cmp_lt_u32_e32 vcc, s2, v189
	global_store_dwordx2 v152, v[150:151], s[50:51]
	s_and_b64 exec, exec, vcc
	s_cbranch_execz .LBB0_3114
	v_add_u32_e32 v150, s14, v189
	v_mul_lo_u32 v150, v150, s90
	v_add_lshl_u32 v150, v150, v196, 2
	global_store_dwordx4 v150, v[146:149], s[58:59]
.LBB0_3114:
	s_or_b64 exec, exec, s[0:1]
	v_mov_b32_e32 v189, v97
	v_lshl_add_u64 v[146:147], s[48:49], 0, v[188:189]
	v_mov_b32_e32 v150, v240
	v_pk_mul_f32 v[148:149], v[56:57], v[150:151] op_sel_hi:[1,0]
	v_pk_mul_f32 v[146:147], v[58:59], v[150:151] op_sel_hi:[1,0]
	v_pk_mul_f32 v[178:179], v[50:51], v[150:151] op_sel_hi:[1,0]
	v_pk_mul_f32 v[180:181], v[48:49], v[150:151] op_sel_hi:[1,0]
	v_mov_b32_e32 v182, 0
	v_mov_b32_dpp v182, v148 row_shr:1 row_mask:0xf bank_mask:0xf
	v_mov_b32_e32 v186, 0
	v_mov_b32_dpp v186, v148 row_shr:2 row_mask:0xf bank_mask:0xf
	v_mov_b32_e32 v183, 0
	v_mov_b32_dpp v183, v149 row_shr:1 row_mask:0xf bank_mask:0xf
	v_mov_b32_e32 v187, 0
	v_mov_b32_dpp v187, v149 row_shr:2 row_mask:0xf bank_mask:0xf
	v_mov_b32_e32 v184, 0
	v_mov_b32_dpp v184, v146 row_shr:1 row_mask:0xf bank_mask:0xf
	v_mov_b32_e32 v188, 0
	v_mov_b32_dpp v188, v146 row_shr:2 row_mask:0xf bank_mask:0xf
	v_mov_b32_e32 v185, 0
	v_mov_b32_dpp v185, v147 row_shr:1 row_mask:0xf bank_mask:0xf
	v_mov_b32_e32 v189, 0
	v_mov_b32_dpp v189, v147 row_shr:2 row_mask:0xf bank_mask:0xf
	s_and_saveexec_b64 s[0:1], s[40:41]
	s_xor_b64 s[0:1], exec, s[0:1]
	s_cbranch_execz .LBB0_3116
	v_pk_fma_f32 v[150:151], v[130:131], v[186:187], v[142:143]
	s_nop 0
	v_pk_fma_f32 v[150:151], v[138:139], v[182:183], v[150:151]
	v_pk_fma_f32 v[182:183], v[132:133], v[188:189], v[144:145]
	v_pk_fma_f32 v[150:151], v[134:135], v[148:149], v[150:151]
	v_pk_fma_f32 v[182:183], v[140:141], v[184:185], v[182:183]
	v_mul_f32_e32 v96, 0xbfb8aa3b, v150
	v_exp_f32_e32 v96, v96
	v_mul_f32_e32 v152, 0xbfb8aa3b, v151
	v_exp_f32_e32 v152, v152
	v_pk_fma_f32 v[182:183], v[136:137], v[146:147], v[182:183]
	v_add_f32_e32 v96, 1.0, v96
	v_mul_f32_e32 v184, 0xbfb8aa3b, v183
	v_add_f32_e32 v153, 1.0, v152
	v_rcp_f32_e32 v152, v96
	v_mul_f32_e32 v96, 0xbfb8aa3b, v182
	v_exp_f32_e32 v96, v96
	v_exp_f32_e32 v185, v184
	v_rcp_f32_e32 v153, v153
	v_add_f32_e32 v96, 1.0, v96
	v_rcp_f32_e32 v184, v96
	v_add_f32_e32 v96, 1.0, v185
	v_rcp_f32_e32 v185, v96
	v_pk_mul_f32 v[150:151], v[150:151], v[152:153]
	v_add_lshl_u32 v96, v231, v196, 1
	v_pk_mul_f32 v[150:151], v[180:181], v[150:151]
	v_pk_mul_f32 v[152:153], v[182:183], v[184:185]
	v_cvt_pk_bf16_f32 v150, v150, v151
	v_pk_mul_f32 v[152:153], v[178:179], v[152:153]
	s_nop 0
	v_cvt_pk_bf16_f32 v151, v152, v153
	global_store_dwordx2 v96, v[150:151], s[46:47]

; DI unsigned pk2(float lo, float hi) { f32x2 v = {lo, hi}; bf16x2_t b = __builtin_convertvector(v, bf16x2_t); return __builtin_bit_cast(unsigned, b); }
; DI float silu_f(float x) { return x * __builtin_amdgcn_rcpf(1.f + __builtin_amdgcn_exp2f(-LOG2E * x)); }
; DI float rstd_of(float ssq, float inv_n) { return 1.0f / sqrtf(ssq * inv_n + EPS); }
; DI float acc_get_i(const acc_t* base, unsigned idx, float inv_scale) { return (float)(*(const acc_t*)((const char*)base + idx * 8u)) * inv_scale; }
; template <class T> DI T* boff(T* base, unsigned byte_off) { return (T*)((char*)base + byte_off); }
;     DI void operator()(const f32x4 (&acc)[2][2][4][2], const Unit& u, int wr, int wc, int fr, int fq) const {
;     ...
;                 for (int m = 0; m < 4; ++m) { const int row = u.pm * BM + ai * HALF + wr * 64 + m * 16 + fr;
;                     const float rs = rstd_of(acc_get_i(ssq, (unsigned)row, 1.0f / SSQ_SCALE), 1.0f / DM);
;                     const f32x4 g = acc[ai][0][m][n] * rs, up = acc[ai][1][m][n] * rs;
;                     f32x4 a;
; #pragma unroll
;                     for (int j = 0; j < 4; ++j) { const float s1 = __shfl(fr == 15 ? pg[j] : g[j], src1), s2 = __shfl(fr >= 14 ? pg[j] : g[j], src2);
;                         a[j] = silu_f(cbv[j] + w0[j] * s2 + w1[j] * s1 + w2[j] * g[j]) * up[j]; }
;                     u32x2 gw; gw.x = pk2(g[0], g[1]); gw.y = pk2(g[2], g[3]);
;                     if (m == 0 && fr < 2) {
;                         *boff((u32x2*)GS, (unsigned)(((row >> 6) * 4 + 2 + fr) * DFF + c4) * 2u) = gw;
;                         u32x2 uw; uw.x = pk2(up[0], up[1]); uw.y = pk2(up[2], up[3]); *boff((u32x2*)US, (unsigned)(((row >> 6) * 2 + fr) * DFF + c4) * 2u) = uw;
;                     } else { u32x2 w; w.x = pk2(a[0], a[1]); w.y = pk2(a[2], a[3]); *boff((u32x2*)A2, (unsigned)(row * DFF + c4) * 2u) = w; }
;                     if (m == 3 && fr >= 14) {
;                         *boff((u32x2*)GS, (unsigned)(((row >> 6) * 4 + (fr - 14)) * DFF + c4) * 2u) = gw;
;                         if ((row & (SEQ - 1)) >= SEQ - 2) *boff((f32x4*)fcp, (unsigned)(((row >> 11) * 2 + ((row & (SEQ - 1)) - (SEQ - 2))) * DFF + c4) * 4u) = g;
;                     }
.LBB0_3118:
	s_or_b64 exec, exec, s[0:1]
	v_mov_b32_e32 v191, v97
	v_lshl_add_u64 v[150:151], s[48:49], 0, v[190:191]
	v_add_lshl_u32 v188, v195, v196, 1
	v_mov_b32_e32 v193, v97
	v_mov_b32_e32 v195, v97
	v_mov_b32_e32 v96, v241
	v_pk_mul_f32 v[150:151], v[42:43], v[96:97] op_sel_hi:[1,0]
	v_pk_mul_f32 v[152:153], v[40:41], v[96:97] op_sel_hi:[1,0]
	v_mov_b32_dpp v178, v146 row_ror:2 row_mask:0xf bank_mask:0xf
	v_mov_b32_dpp v178, v150 row_shr:2 row_mask:0xf bank_mask:0xf
	v_mov_b32_dpp v179, v147 row_ror:2 row_mask:0xf bank_mask:0xf
	v_mov_b32_dpp v179, v151 row_shr:2 row_mask:0xf bank_mask:0xf
	v_mov_b32_dpp v180, v146 row_ror:1 row_mask:0xf bank_mask:0xf
	v_mov_b32_dpp v180, v150 row_shr:1 row_mask:0xf bank_mask:0xf
	v_mov_b32_dpp v181, v147 row_ror:1 row_mask:0xf bank_mask:0xf
	v_mov_b32_dpp v181, v151 row_shr:1 row_mask:0xf bank_mask:0xf
	v_mov_b32_dpp v146, v148 row_ror:1 row_mask:0xf bank_mask:0xf
	v_mov_b32_dpp v146, v152 row_shr:1 row_mask:0xf bank_mask:0xf
	v_mov_b32_dpp v148, v148 row_ror:2 row_mask:0xf bank_mask:0xf
	v_mov_b32_dpp v148, v152 row_shr:2 row_mask:0xf bank_mask:0xf
	v_mov_b32_dpp v147, v149 row_ror:1 row_mask:0xf bank_mask:0xf
	v_mov_b32_dpp v147, v153 row_shr:1 row_mask:0xf bank_mask:0xf
	v_mov_b32_dpp v149, v149 row_ror:2 row_mask:0xf bank_mask:0xf
	v_mov_b32_dpp v149, v153 row_shr:2 row_mask:0xf bank_mask:0xf
	v_pk_fma_f32 v[148:149], v[130:131], v[148:149], v[142:143]
	v_pk_mul_f32 v[184:185], v[34:35], v[96:97] op_sel_hi:[1,0]
	v_pk_fma_f32 v[178:179], v[132:133], v[178:179], v[144:145]
	v_pk_fma_f32 v[146:147], v[138:139], v[146:147], v[148:149]
	v_pk_fma_f32 v[148:149], v[140:141], v[180:181], v[178:179]
	v_pk_fma_f32 v[146:147], v[134:135], v[152:153], v[146:147]
	v_pk_fma_f32 v[148:149], v[136:137], v[150:151], v[148:149]
	v_mul_f32_e32 v178, 0xbfb8aa3b, v146
	v_mul_f32_e32 v179, 0xbfb8aa3b, v147
	v_mul_f32_e32 v180, 0xbfb8aa3b, v148
	v_mul_f32_e32 v181, 0xbfb8aa3b, v149
	v_exp_f32_e32 v178, v178
	v_exp_f32_e32 v179, v179
	v_exp_f32_e32 v180, v180
	v_exp_f32_e32 v181, v181
	v_add_f32_e32 v178, 1.0, v178
	v_add_f32_e32 v179, 1.0, v179
	v_add_f32_e32 v180, 1.0, v180
	v_add_f32_e32 v181, 1.0, v181
	v_rcp_f32_e32 v178, v178
	v_rcp_f32_e32 v179, v179
	v_rcp_f32_e32 v180, v180
	v_rcp_f32_e32 v181, v181
	v_pk_mul_f32 v[186:187], v[32:33], v[96:97] op_sel_hi:[1,0]
	v_pk_mul_f32 v[146:147], v[146:147], v[178:179]
	v_lshl_add_u64 v[182:183], s[48:49], 0, v[192:193]
	v_pk_mul_f32 v[148:149], v[148:149], v[180:181]
	v_pk_mul_f32 v[146:147], v[186:187], v[146:147]
	v_pk_mul_f32 v[148:149], v[184:185], v[148:149]
	v_cvt_pk_bf16_f32 v146, v146, v147
	v_cvt_pk_bf16_f32 v147, v148, v149
	global_store_dwordx2 v188, v[146:147], s[46:47]
	v_add_lshl_u32 v188, v233, v196, 1
	v_mov_b32_e32 v96, v242
	v_pk_mul_f32 v[178:179], v[26:27], v[96:97] op_sel_hi:[1,0]
	v_pk_mul_f32 v[180:181], v[24:25], v[96:97] op_sel_hi:[1,0]
	v_mov_b32_dpp v148, v152 row_ror:2 row_mask:0xf bank_mask:0xf
	s_nop 0
	v_mov_b32_dpp v148, v180 row_shr:2 row_mask:0xf bank_mask:0xf
	v_mov_b32_dpp v147, v153 row_ror:1 row_mask:0xf bank_mask:0xf
	v_mov_b32_dpp v147, v181 row_shr:1 row_mask:0xf bank_mask:0xf
	v_mov_b32_dpp v149, v153 row_ror:2 row_mask:0xf bank_mask:0xf
	v_mov_b32_dpp v149, v181 row_shr:2 row_mask:0xf bank_mask:0xf
	v_mov_b32_dpp v146, v152 row_ror:1 row_mask:0xf bank_mask:0xf
	v_mov_b32_dpp v146, v180 row_shr:1 row_mask:0xf bank_mask:0xf
	v_mov_b32_dpp v152, v150 row_ror:1 row_mask:0xf bank_mask:0xf
	v_mov_b32_dpp v152, v178 row_shr:1 row_mask:0xf bank_mask:0xf
	v_mov_b32_dpp v153, v151 row_ror:1 row_mask:0xf bank_mask:0xf
	v_mov_b32_dpp v153, v179 row_shr:1 row_mask:0xf bank_mask:0xf
	v_mov_b32_dpp v150, v150 row_ror:2 row_mask:0xf bank_mask:0xf
	v_mov_b32_dpp v150, v178 row_shr:2 row_mask:0xf bank_mask:0xf
	v_mov_b32_dpp v151, v151 row_ror:2 row_mask:0xf bank_mask:0xf
	v_mov_b32_dpp v151, v179 row_shr:2 row_mask:0xf bank_mask:0xf
	v_pk_fma_f32 v[148:149], v[130:131], v[148:149], v[142:143]
	v_pk_fma_f32 v[150:151], v[132:133], v[150:151], v[144:145]
	v_pk_fma_f32 v[146:147], v[138:139], v[146:147], v[148:149]
; DI unsigned pk2(float lo, float hi) { f32x2 v = {lo, hi}; bf16x2_t b = __builtin_convertvector(v, bf16x2_t); return __builtin_bit_cast(unsigned, b); }
; DI float silu_f(float x) { return x * __builtin_amdgcn_rcpf(1.f + __builtin_amdgcn_exp2f(-LOG2E * x)); }
; DI float rstd_of(float ssq, float inv_n) { return 1.0f / sqrtf(ssq * inv_n + EPS); }
; DI float acc_get_i(const acc_t* base, unsigned idx, float inv_scale) { return (float)(*(const acc_t*)((const char*)base + idx * 8u)) * inv_scale; }
; template <class T> DI T* boff(T* base, unsigned byte_off) { return (T*)((char*)base + byte_off); }
;     DI void operator()(const f32x4 (&acc)[2][2][4][2], const Unit& u, int wr, int wc, int fr, int fq) const {
;     ...
;                 for (int m = 0; m < 4; ++m) { const int row = u.pm * BM + ai * HALF + wr * 64 + m * 16 + fr;
;                     const float rs = rstd_of(acc_get_i(ssq, (unsigned)row, 1.0f / SSQ_SCALE), 1.0f / DM);
;                     const f32x4 g = acc[ai][0][m][n] * rs, up = acc[ai][1][m][n] * rs;
;                     f32x4 a;
; #pragma unroll
;                     for (int j = 0; j < 4; ++j) { const float s1 = __shfl(fr == 15 ? pg[j] : g[j], src1), s2 = __shfl(fr >= 14 ? pg[j] : g[j], src2);
;                         a[j] = silu_f(cbv[j] + w0[j] * s2 + w1[j] * s1 + w2[j] * g[j]) * up[j]; }
;                     u32x2 gw; gw.x = pk2(g[0], g[1]); gw.y = pk2(g[2], g[3]);
;                     if (m == 0 && fr < 2) {
;                         *boff((u32x2*)GS, (unsigned)(((row >> 6) * 4 + 2 + fr) * DFF + c4) * 2u) = gw;
;                         u32x2 uw; uw.x = pk2(up[0], up[1]); uw.y = pk2(up[2], up[3]); *boff((u32x2*)US, (unsigned)(((row >> 6) * 2 + fr) * DFF + c4) * 2u) = uw;
;                     } else { u32x2 w; w.x = pk2(a[0], a[1]); w.y = pk2(a[2], a[3]); *boff((u32x2*)A2, (unsigned)(row * DFF + c4) * 2u) = w; }
;                     if (m == 3 && fr >= 14) {
;                         *boff((u32x2*)GS, (unsigned)(((row >> 6) * 4 + (fr - 14)) * DFF + c4) * 2u) = gw;
;                         if ((row & (SEQ - 1)) >= SEQ - 2) *boff((f32x4*)fcp, (unsigned)(((row >> 11) * 2 + ((row & (SEQ - 1)) - (SEQ - 2))) * DFF + c4) * 4u) = g;
;                     }
	v_pk_mul_f32 v[184:185], v[18:19], v[96:97] op_sel_hi:[1,0]
	v_pk_fma_f32 v[148:149], v[140:141], v[152:153], v[150:151]
	v_pk_fma_f32 v[146:147], v[134:135], v[180:181], v[146:147]
	v_pk_fma_f32 v[148:149], v[136:137], v[178:179], v[148:149]
	v_mul_f32_e32 v150, 0xbfb8aa3b, v146
	v_mul_f32_e32 v151, 0xbfb8aa3b, v147
	v_mul_f32_e32 v152, 0xbfb8aa3b, v148
	v_mul_f32_e32 v153, 0xbfb8aa3b, v149
	v_exp_f32_e32 v150, v150
	v_exp_f32_e32 v151, v151
	v_exp_f32_e32 v152, v152
	v_exp_f32_e32 v153, v153
	v_add_f32_e32 v150, 1.0, v150
	v_add_f32_e32 v151, 1.0, v151
	v_add_f32_e32 v152, 1.0, v152
	v_add_f32_e32 v153, 1.0, v153
	v_rcp_f32_e32 v150, v150
	v_rcp_f32_e32 v151, v151
	v_rcp_f32_e32 v152, v152
	v_rcp_f32_e32 v153, v153
	v_pk_mul_f32 v[186:187], v[16:17], v[96:97] op_sel_hi:[1,0]
	v_pk_mul_f32 v[146:147], v[146:147], v[150:151]
	v_lshl_add_u64 v[182:183], s[48:49], 0, v[194:195]
	v_pk_mul_f32 v[148:149], v[148:149], v[152:153]
	v_pk_mul_f32 v[146:147], v[186:187], v[146:147]
	v_pk_mul_f32 v[148:149], v[184:185], v[148:149]
	v_cvt_pk_bf16_f32 v146, v146, v147
	v_cvt_pk_bf16_f32 v147, v148, v149
	global_store_dwordx2 v188, v[146:147], s[46:47]
	v_mov_b32_e32 v96, v243
	v_pk_mul_f32 v[148:149], v[10:11], v[96:97] op_sel_hi:[1,0]
	v_pk_mul_f32 v[146:147], v[8:9], v[96:97] op_sel_hi:[1,0]
	v_mov_b32_dpp v152, v180 row_ror:2 row_mask:0xf bank_mask:0xf
	s_nop 0
	v_mov_b32_dpp v152, v146 row_shr:2 row_mask:0xf bank_mask:0xf
	v_mov_b32_dpp v151, v181 row_ror:1 row_mask:0xf bank_mask:0xf
	v_mov_b32_dpp v151, v147 row_shr:1 row_mask:0xf bank_mask:0xf
	v_mov_b32_dpp v153, v181 row_ror:2 row_mask:0xf bank_mask:0xf
	v_mov_b32_dpp v153, v147 row_shr:2 row_mask:0xf bank_mask:0xf
	v_mov_b32_dpp v150, v180 row_ror:1 row_mask:0xf bank_mask:0xf
	v_mov_b32_dpp v150, v146 row_shr:1 row_mask:0xf bank_mask:0xf
	v_mov_b32_dpp v180, v178 row_ror:1 row_mask:0xf bank_mask:0xf
	v_mov_b32_dpp v180, v148 row_shr:1 row_mask:0xf bank_mask:0xf
	v_mov_b32_dpp v181, v179 row_ror:1 row_mask:0xf bank_mask:0xf
	v_mov_b32_dpp v181, v149 row_shr:1 row_mask:0xf bank_mask:0xf
	v_mov_b32_dpp v178, v178 row_ror:2 row_mask:0xf bank_mask:0xf
	v_mov_b32_dpp v178, v148 row_shr:2 row_mask:0xf bank_mask:0xf
	v_mov_b32_dpp v179, v179 row_ror:2 row_mask:0xf bank_mask:0xf
	v_mov_b32_dpp v179, v149 row_shr:2 row_mask:0xf bank_mask:0xf
	v_pk_fma_f32 v[130:131], v[130:131], v[152:153], v[142:143]
	v_pk_fma_f32 v[132:133], v[132:133], v[178:179], v[144:145]
	v_pk_fma_f32 v[130:131], v[138:139], v[150:151], v[130:131]
	v_pk_mul_f32 v[138:139], v[2:3], v[96:97] op_sel_hi:[1,0]
	v_pk_fma_f32 v[132:133], v[140:141], v[180:181], v[132:133]
	v_pk_fma_f32 v[130:131], v[134:135], v[146:147], v[130:131]
	v_pk_fma_f32 v[132:133], v[136:137], v[148:149], v[132:133]
	v_mul_f32_e32 v134, 0xbfb8aa3b, v130
	v_mul_f32_e32 v135, 0xbfb8aa3b, v131
	v_mul_f32_e32 v136, 0xbfb8aa3b, v132
	v_mul_f32_e32 v137, 0xbfb8aa3b, v133
	v_exp_f32_e32 v134, v134
	v_exp_f32_e32 v135, v135
	v_exp_f32_e32 v136, v136
	v_exp_f32_e32 v137, v137
	v_add_f32_e32 v134, 1.0, v134
	v_add_f32_e32 v135, 1.0, v135
	v_add_f32_e32 v136, 1.0, v136
	v_add_f32_e32 v137, 1.0, v137
	v_rcp_f32_e32 v134, v134
	v_rcp_f32_e32 v135, v135
	v_rcp_f32_e32 v136, v136
	v_rcp_f32_e32 v137, v137
	v_pk_mul_f32 v[140:141], v[0:1], v[96:97] op_sel_hi:[1,0]
	v_pk_mul_f32 v[130:131], v[130:131], v[134:135]
	v_add_lshl_u32 v96, v234, v196, 1
	v_pk_mul_f32 v[132:133], v[132:133], v[136:137]
	v_pk_mul_f32 v[130:131], v[140:141], v[130:131]
	v_pk_mul_f32 v[132:133], v[138:139], v[132:133]
	v_cvt_pk_bf16_f32 v130, v130, v131
	v_cvt_pk_bf16_f32 v131, v132, v133
	global_store_dwordx2 v96, v[130:131], s[46:47]
	s_and_saveexec_b64 s[0:1], s[38:39]
	s_cbranch_execz .LBB0_3121
	s_movk_i32 s2, 0x7fd
	v_add_lshl_u32 v96, v221, v196, 1
	v_cvt_pk_bf16_f32 v130, v146, v147
	v_cvt_pk_bf16_f32 v131, v148, v149
	v_cmp_lt_u32_e32 vcc, s2, v235
	global_store_dwordx2 v96, v[130:131], s[50:51]
	s_and_b64 exec, exec, vcc
	s_cbranch_execz .LBB0_3121
	v_add_u32_e32 v96, s15, v235
	v_mul_lo_u32 v96, v96, s90
	v_add_lshl_u32 v96, v96, v196, 2
	global_store_dwordx4 v96, v[146:149], s[58:59]
